# attention item prologue: count/index/query loads issued together, index list padded once so gathers need no clamp, K/V gather via scalar base + 32-bit offsets with batched index reads
# speedup vs baseline: 1.0081x; 1.0059x over previous
; __device__ __forceinline__ void dsa_attend(const h16* PROJ, const unsigned short* IDX, const int* CNT, h16* MIXA, unsigned char* shm, unsigned* bar, unsigned xcc, unsigned xrank) {
;     ...
;         const int b = u >> 1, g = u & 1, tokbase = b * SEQ;
;         for (int it = rank; it < 1024; it += total) {
;             const int t = it * 8 + wid, tokq = tokbase + t; int nsel = __builtin_amdgcn_readfirstlane(CNT[tokq]); nsel = nsel < 1 ? 1 : (nsel > 256 ? 256 : nsel);
;     ...
;             const unsigned char* kbase8 = (const unsigned char*)(PROJ + O_KG) + (size_t)(b * 2 + g) * SEQ * 128 + 16 * fq;
;             {
;                 uint4 kf[16][2];
; #pragma unroll
;                 for (int e = 0; e < 16; ++e) { const int slot = 16 * e + fr; const int idx = (int)sel[qq * 256 + (slot < nsel ? slot : nsel - 1)];
;                     const unsigned char* krow = kbase8 + (size_t)idx * 128;
;                     kf[e][0] = *(const uint4*)krow; kf[e][1] = *(const uint4*)(krow + 64); }
;                 __builtin_amdgcn_sched_barrier(0);
; #pragma unroll
;                 for (int e = 0; e < 16; ++e) {
;                     f32x4 a = (f32x4){0.f, 0.f, 0.f, 0.f};
; #pragma unroll
;                     for (int L = 0; L < 2; ++L) {
;                         const long k0 = (long)(((unsigned long long)kf[e][L].y << 32) | (unsigned long long)kf[e][L].x), k1 = (long)(((unsigned long long)kf[e][L].w << 32) | (unsigned long long)kf[e][L].z);
;                         a = __builtin_amdgcn_mfma_f32_16x16x32_fp8_fp8(qa8[2 * L], k0, a, 0, 0, 0); a = __builtin_amdgcn_mfma_f32_16x16x32_fp8_fp8(qa8[2 * L + 1], k1, a, 0, 0, 0); }
;                     if (16 * e + fr >= nsel) a = (f32x4){-1e30f, -1e30f, -1e30f, -1e30f};
;                     sacc[e] = a; }
;                 __builtin_amdgcn_sched_barrier(0);
;             }
;             f32x4 mx = sacc[0];
; #pragma unroll
;             for (int jt = 1; jt < 16; ++jt)
; #pragma unroll
;                 for (int i = 0; i < 4; ++i) mx[i] = fmaxf(mx[i], sacc[jt][i]);
; #pragma unroll
;             for (int o = 1; o < 16; o <<= 1)
; #pragma unroll
;                 for (int i = 0; i < 4; ++i) mx[i] = fmaxf(mx[i], __shfl_xor(mx[i], o));
;             f32x4 sm = (f32x4){0.f, 0.f, 0.f, 0.f};
;             const float sc = 0.08838834764831845f;
; #pragma unroll
;             for (int jt = 0; jt < 16; ++jt)
; #pragma unroll
.LBB0_841:
	s_movk_i32 s60, 0x400
	v_cmp_gt_i32_e32 vcc, s60, v220
	s_and_b64 s[50:51], s[50:51], vcc
	s_andn2_b64 vcc, exec, s[50:51]
	s_cbranch_vccnz .LBB0_808
	s_lshl_b32 s50, s83, 12
	s_and_b32 s50, s50, 0x6000
	v_add_u32_e32 v221, s50, v188
	s_lshl_b32 s50, s83, 9
	s_and_b32 s50, s50, 0x200
	s_lshl_b32 s70, s83, 20
	v_add_lshl_u32 v162, s50, v192, 1
	v_lshl_add_u64 v[140:141], v[132:133], 0, s[70:71]
	s_nop 1
	v_readfirstlane_b32 s98, v140
	v_readfirstlane_b32 s99, v141
	v_lshl_add_u32 v240, v189, 1, v190
	v_lshl_add_u32 v241, v193, 1, v190
	v_and_b32_e32 v242, 48, v216
	v_lshlrev_b32_e32 v243, 4, v216
	v_and_b32_e32 v243, 0x70, v243
	v_add_u32_e32 v243, 0x1000000, v243
	v_mov_b32_e32 v244, 0x3e0293ee
	v_lshl_add_u64 v[142:143], v[134:135], 0, s[70:71]
	s_lshl_b32 s70, s50, 1
	v_lshl_add_u64 v[138:139], v[130:131], 0, v[162:163]
	v_lshl_add_u64 v[144:145], v[136:137], 0, s[70:71]
	v_mov_b32_e32 v222, v220
	s_branch .LBB0_844

; __device__ __forceinline__ void dsa_attend(const h16* PROJ, const unsigned short* IDX, const int* CNT, h16* MIXA, unsigned char* shm, unsigned* bar, unsigned xcc, unsigned xrank) {
;     ...
;             const int t = it * 8 + wid, tokq = tokbase + t; int nsel = __builtin_amdgcn_readfirstlane(CNT[tokq]); nsel = nsel < 1 ? 1 : (nsel > 256 ? 256 : nsel);
;             *(unsigned long long*)(sel + 4 * lane) = *(const unsigned long long*)(IDX + (size_t)tokq * 256 + 4 * lane);
;             asm volatile("s_waitcnt vmcnt(0) lgkmcnt(0)" ::: "memory");
;             h16x8 qa[4];
; #pragma unroll
;             for (int kk = 0; kk < 4; ++kk) { h16x8 z;
; #pragma unroll
;                 for (int e = 0; e < 8; ++e) z[e] = (h16)0.f;
;                 qa[kk] = z; }
;             if (fr < 4) { const h16* qrow = PROJ + O_Q + (size_t)tokq * 1024 + (g * 4 + fr) * 128 + 16 * fq;
; #pragma unroll
;                 for (int kk = 0; kk < 4; ++kk) qa[kk] = *(const h16x8*)(qrow + (kk & 1) * 8 + (kk >> 1) * 64); }
;             long qa8[4];
; #pragma unroll
;             for (int kk = 0; kk < 4; ++kk) {
;                 int w0 = __builtin_amdgcn_cvt_pk_fp8_f32((float)qa[kk][0], (float)qa[kk][1], 0, false); w0 = __builtin_amdgcn_cvt_pk_fp8_f32((float)qa[kk][2], (float)qa[kk][3], w0, true);
;                 int w1 = __builtin_amdgcn_cvt_pk_fp8_f32((float)qa[kk][4], (float)qa[kk][5], 0, false); w1 = __builtin_amdgcn_cvt_pk_fp8_f32((float)qa[kk][6], (float)qa[kk][7], w1, true);
;                 qa8[kk] = (long)(((unsigned long long)(unsigned)w1 << 32) | (unsigned long long)(unsigned)w0); }
;             f32x4 sacc[16];
;             const unsigned char* kbase8 = (const unsigned char*)(PROJ + O_KG) + (size_t)(b * 2 + g) * SEQ * 128 + 16 * fq;
;             {
;                 uint4 kf[16][2];
; #pragma unroll
;                 for (int e = 0; e < 16; ++e) { const int slot = 16 * e + fr; const int idx = (int)sel[qq * 256 + (slot < nsel ? slot : nsel - 1)];
;                     const unsigned char* krow = kbase8 + (size_t)idx * 128;
;                     kf[e][0] = *(const uint4*)krow; kf[e][1] = *(const uint4*)(krow + 64); }
.LBB0_844:
	v_lshl_add_u32 v0, v222, 3, v221
	v_ashrrev_i32_e32 v1, 31, v0
	v_lshl_add_u64 v[2:3], v[0:1], 2, s[56:57]
	global_load_dword v148, v[2:3], off
	v_lshlrev_b64 v[2:3], 9, v[0:1]
	v_lshl_add_u64 v[2:3], v[128:129], 0, v[2:3]
	global_load_dwordx2 v[150:151], v[2:3], off
	s_waitcnt lgkmcnt(14)
	v_lshlrev_b64 v[146:147], 11, v[0:1]
	v_mov_b32_e32 v12, 0
	v_mov_b32_e32 v13, 0
	v_mov_b32_e32 v14, 0
	v_mov_b32_e32 v15, 0
	v_mov_b32_e32 v8, 0
	v_mov_b32_e32 v9, 0
	v_mov_b32_e32 v10, 0
	v_mov_b32_e32 v11, 0
	v_mov_b32_e32 v4, 0
	v_mov_b32_e32 v5, 0
	v_mov_b32_e32 v6, 0
	v_mov_b32_e32 v7, 0
	v_mov_b32_e32 v0, 0
	v_mov_b32_e32 v1, 0
	v_mov_b32_e32 v2, 0
	v_mov_b32_e32 v3, 0
	s_and_saveexec_b64 s[50:51], s[44:45]
	s_cbranch_execz .Lmy_att_noq
	v_lshl_add_u64 v[4:5], v[138:139], 0, v[146:147]
	global_load_dwordx4 v[12:15], v[4:5], off
	global_load_dwordx4 v[8:11], v[4:5], off offset:16
	global_load_dwordx4 v[0:3], v[4:5], off offset:128
	s_nop 0
	global_load_dwordx4 v[4:7], v[4:5], off offset:144
.Lmy_att_noq:
	s_or_b64 exec, exec, s[50:51]
	s_waitcnt vmcnt(0)
	v_readfirstlane_b32 s67, v148
	ds_write_b64 v191, v[150:151] offset:32768
	s_waitcnt vmcnt(0) lgkmcnt(0)
	s_max_i32 s50, s67, 1
	s_min_i32 s50, s50, 0x100
	s_cmp_eq_u32 s50, 0x100
	s_cbranch_scc1 .Lmy_att_full
	s_add_i32 s50, s50, -1
	v_mov_b32_e32 v245, s50
	v_lshl_add_u32 v245, v245, 1, v190
	ds_read_u16 v245, v245 offset:32768
	v_lshlrev_b32_e32 v246, 2, v216
	v_add_u32_e32 v249, 2, v246
	s_waitcnt lgkmcnt(0)
	v_lshlrev_b32_e32 v248, 16, v245
	v_and_b32_e32 v247, 0xffff0000, v150
	v_or_b32_e32 v247, v247, v245
	v_cmp_lt_u32_e32 vcc, s50, v246
	s_nop 1
	v_cndmask_b32_e32 v150, v150, v247, vcc
	v_and_b32_e32 v247, 0xffff, v150
	v_or_b32_e32 v247, v247, v248
	v_cmp_le_u32_e32 vcc, s50, v246
	s_nop 1
	v_cndmask_b32_e32 v150, v150, v247, vcc
	v_and_b32_e32 v247, 0xffff0000, v151
	v_or_b32_e32 v247, v247, v245
	v_cmp_lt_u32_e32 vcc, s50, v249
	s_nop 1
	v_cndmask_b32_e32 v151, v151, v247, vcc
	v_and_b32_e32 v247, 0xffff, v151
	v_or_b32_e32 v247, v247, v248
	v_cmp_le_u32_e32 vcc, s50, v249
	s_nop 1
	v_cndmask_b32_e32 v151, v151, v247, vcc
	ds_write_b64 v191, v[150:151] offset:32768
	s_waitcnt lgkmcnt(0)
.Lmy_att_full:
	s_waitcnt vmcnt(3)
	v_cvt_f32_f16_e32 v16, v12
	v_cvt_f32_f16_sdwa v12, v12 dst_sel:DWORD dst_unused:UNUSED_PAD src0_sel:WORD_1
	v_mov_b32_e32 v148, v163
	v_mov_b32_e32 v149, v163
	v_mov_b32_e32 v150, v163
	v_cvt_pk_fp8_f32 v148, v16, v12
	v_cvt_f32_f16_e32 v12, v13
	v_cvt_f32_f16_sdwa v13, v13 dst_sel:DWORD dst_unused:UNUSED_PAD src0_sel:WORD_1
	v_mov_b32_e32 v151, v163
	v_mov_b32_e32 v152, v163
	v_mov_b32_e32 v153, v163
	v_cvt_pk_fp8_f32 v148, v12, v13 op_sel:[0,0,1]
	v_cvt_f32_f16_e32 v12, v14
	v_cvt_f32_f16_sdwa v13, v14 dst_sel:DWORD dst_unused:UNUSED_PAD src0_sel:WORD_1
	v_mov_b32_e32 v154, v163
	v_mov_b32_e32 v155, v163
	s_max_i32 s50, s67, 1
	v_cvt_pk_fp8_f32 v149, v12, v13
	v_cvt_f32_f16_e32 v12, v15
	v_cvt_f32_f16_sdwa v13, v15 dst_sel:DWORD dst_unused:UNUSED_PAD src0_sel:WORD_1
	s_min_i32 s67, s50, 0x100
	s_add_i32 s70, s67, -1
	v_cvt_pk_fp8_f32 v149, v12, v13 op_sel:[0,0,1]
	s_waitcnt vmcnt(2)
	v_cvt_f32_f16_e32 v12, v8
	v_cvt_f32_f16_sdwa v8, v8 dst_sel:DWORD dst_unused:UNUSED_PAD src0_sel:WORD_1
	v_cvt_pk_fp8_f32 v150, v12, v8
	v_cvt_f32_f16_e32 v8, v9
	v_cvt_f32_f16_sdwa v9, v9 dst_sel:DWORD dst_unused:UNUSED_PAD src0_sel:WORD_1
	v_cvt_pk_fp8_f32 v150, v8, v9 op_sel:[0,0,1]
	v_cvt_f32_f16_e32 v8, v10
	v_cvt_f32_f16_sdwa v9, v10 dst_sel:DWORD dst_unused:UNUSED_PAD src0_sel:WORD_1
	v_cvt_pk_fp8_f32 v151, v8, v9
	v_cvt_f32_f16_e32 v8, v11
	v_cvt_f32_f16_sdwa v9, v11 dst_sel:DWORD dst_unused:UNUSED_PAD src0_sel:WORD_1
	s_waitcnt lgkmcnt(8)
	v_cvt_pk_fp8_f32 v151, v8, v9 op_sel:[0,0,1]
	s_waitcnt vmcnt(1)
	v_cvt_f32_f16_e32 v8, v0
	v_cvt_f32_f16_sdwa v0, v0 dst_sel:DWORD dst_unused:UNUSED_PAD src0_sel:WORD_1
	v_cvt_pk_fp8_f32 v152, v8, v0
	v_cvt_f32_f16_e32 v0, v1
	v_cvt_f32_f16_sdwa v1, v1 dst_sel:DWORD dst_unused:UNUSED_PAD src0_sel:WORD_1
	v_cvt_pk_fp8_f32 v152, v0, v1 op_sel:[0,0,1]
	v_cvt_f32_f16_e32 v0, v2
	v_cvt_f32_f16_sdwa v1, v2 dst_sel:DWORD dst_unused:UNUSED_PAD src0_sel:WORD_1
	v_cvt_pk_fp8_f32 v153, v0, v1
	v_cvt_f32_f16_e32 v0, v3
	v_cvt_f32_f16_sdwa v1, v3 dst_sel:DWORD dst_unused:UNUSED_PAD src0_sel:WORD_1
	v_cvt_pk_fp8_f32 v153, v0, v1 op_sel:[0,0,1]
	s_waitcnt vmcnt(0)
	v_cvt_f32_f16_e32 v0, v4
	v_cvt_f32_f16_sdwa v1, v4 dst_sel:DWORD dst_unused:UNUSED_PAD src0_sel:WORD_1
	v_cvt_pk_fp8_f32 v154, v0, v1
	v_cvt_f32_f16_e32 v0, v5
	v_cvt_f32_f16_sdwa v1, v5 dst_sel:DWORD dst_unused:UNUSED_PAD src0_sel:WORD_1
	v_cvt_pk_fp8_f32 v154, v0, v1 op_sel:[0,0,1]
	v_cvt_f32_f16_e32 v0, v6
	v_cvt_f32_f16_sdwa v1, v6 dst_sel:DWORD dst_unused:UNUSED_PAD src0_sel:WORD_1
	v_cvt_pk_fp8_f32 v155, v0, v1
	v_cvt_f32_f16_e32 v0, v7
	v_cvt_f32_f16_sdwa v1, v7 dst_sel:DWORD dst_unused:UNUSED_PAD src0_sel:WORD_1
	v_cvt_pk_fp8_f32 v155, v0, v1 op_sel:[0,0,1]
	ds_read_u16 v0, v240 offset:32768
	ds_read_u16 v8, v240 offset:32800
	ds_read_u16 v16, v240 offset:32832
	ds_read_u16 v24, v240 offset:32864
	ds_read_u16 v32, v240 offset:32896
	ds_read_u16 v40, v240 offset:32928
	ds_read_u16 v48, v240 offset:32960
	ds_read_u16 v56, v240 offset:32992
	ds_read_u16 v64, v240 offset:33024
	ds_read_u16 v72, v240 offset:33056
	ds_read_u16 v80, v240 offset:33088
	ds_read_u16 v84, v240 offset:33120
	ds_read_u16 v92, v240 offset:33152
	ds_read_u16 v100, v240 offset:33184
	ds_read_u16 v108, v240 offset:33216
	ds_read_u16 v120, v240 offset:33248
	s_waitcnt lgkmcnt(15)
	v_lshl_add_u32 v0, v0, 7, v242
	global_load_dwordx4 v[4:7], v0, s[98:99]
	s_nop 0
	global_load_dwordx4 v[0:3], v0, s[98:99] offset:64
	s_waitcnt lgkmcnt(14)
; __device__ __forceinline__ void dsa_attend(const h16* PROJ, const unsigned short* IDX, const int* CNT, h16* MIXA, unsigned char* shm, unsigned* bar, unsigned xcc, unsigned xrank) {
;     ...
;                 for (int e = 0; e < 16; ++e) { const int slot = 16 * e + fr; const int idx = (int)sel[qq * 256 + (slot < nsel ? slot : nsel - 1)];
;                     const unsigned char* krow = kbase8 + (size_t)idx * 128;
;                     kf[e][0] = *(const uint4*)krow; kf[e][1] = *(const uint4*)(krow + 64); }
;                 __builtin_amdgcn_sched_barrier(0);
; #pragma unroll
;                 for (int e = 0; e < 16; ++e) {
;                     f32x4 a = (f32x4){0.f, 0.f, 0.f, 0.f};
; #pragma unroll
;                     for (int L = 0; L < 2; ++L) {
;                         const long k0 = (long)(((unsigned long long)kf[e][L].y << 32) | (unsigned long long)kf[e][L].x), k1 = (long)(((unsigned long long)kf[e][L].w << 32) | (unsigned long long)kf[e][L].z);
;                         a = __builtin_amdgcn_mfma_f32_16x16x32_fp8_fp8(qa8[2 * L], k0, a, 0, 0, 0); a = __builtin_amdgcn_mfma_f32_16x16x32_fp8_fp8(qa8[2 * L + 1], k1, a, 0, 0, 0); }
;                     if (16 * e + fr >= nsel) a = (f32x4){-1e30f, -1e30f, -1e30f, -1e30f};
;                     sacc[e] = a; }
	v_lshl_add_u32 v8, v8, 7, v242
	global_load_dwordx4 v[12:15], v8, s[98:99]
	s_nop 0
	global_load_dwordx4 v[8:11], v8, s[98:99] offset:64
	s_waitcnt lgkmcnt(13)
	v_lshl_add_u32 v16, v16, 7, v242
	global_load_dwordx4 v[20:23], v16, s[98:99]
	s_nop 0
	global_load_dwordx4 v[16:19], v16, s[98:99] offset:64
	s_waitcnt lgkmcnt(12)
	v_lshl_add_u32 v24, v24, 7, v242
	global_load_dwordx4 v[28:31], v24, s[98:99]
	s_nop 0
	global_load_dwordx4 v[24:27], v24, s[98:99] offset:64
	s_waitcnt lgkmcnt(11)
	v_lshl_add_u32 v32, v32, 7, v242
	global_load_dwordx4 v[36:39], v32, s[98:99]
	s_nop 0
	global_load_dwordx4 v[32:35], v32, s[98:99] offset:64
	s_waitcnt lgkmcnt(10)
	v_lshl_add_u32 v40, v40, 7, v242
	global_load_dwordx4 v[44:47], v40, s[98:99]
	s_nop 0
	global_load_dwordx4 v[40:43], v40, s[98:99] offset:64
	s_waitcnt lgkmcnt(9)
	v_lshl_add_u32 v48, v48, 7, v242
	global_load_dwordx4 v[52:55], v48, s[98:99]
	s_nop 0
	global_load_dwordx4 v[48:51], v48, s[98:99] offset:64
	s_waitcnt lgkmcnt(8)
	v_lshl_add_u32 v56, v56, 7, v242
	global_load_dwordx4 v[60:63], v56, s[98:99]
	s_nop 0
	global_load_dwordx4 v[56:59], v56, s[98:99] offset:64
	s_waitcnt lgkmcnt(7)
	v_lshl_add_u32 v64, v64, 7, v242
	global_load_dwordx4 v[68:71], v64, s[98:99]
	s_nop 0
	global_load_dwordx4 v[64:67], v64, s[98:99] offset:64
	s_waitcnt lgkmcnt(6)
	v_lshl_add_u32 v72, v72, 7, v242
	global_load_dwordx4 v[76:79], v72, s[98:99]
	s_nop 0
	global_load_dwordx4 v[72:75], v72, s[98:99] offset:64
	s_waitcnt lgkmcnt(5)
	v_lshl_add_u32 v80, v80, 7, v242
	global_load_dwordx4 v[88:91], v80, s[98:99]
	s_nop 0
	global_load_dwordx4 v[80:83], v80, s[98:99] offset:64
	s_waitcnt lgkmcnt(4)
	v_lshl_add_u32 v84, v84, 7, v242
	global_load_dwordx4 v[96:99], v84, s[98:99]
	s_nop 0
	global_load_dwordx4 v[84:87], v84, s[98:99] offset:64
	s_waitcnt lgkmcnt(3)
	v_lshl_add_u32 v92, v92, 7, v242
	global_load_dwordx4 v[104:107], v92, s[98:99]
	s_nop 0
	global_load_dwordx4 v[92:95], v92, s[98:99] offset:64
	s_waitcnt lgkmcnt(2)
	v_lshl_add_u32 v100, v100, 7, v242
	global_load_dwordx4 v[112:115], v100, s[98:99]
	s_nop 0
	global_load_dwordx4 v[100:103], v100, s[98:99] offset:64
	s_waitcnt lgkmcnt(1)
	v_lshl_add_u32 v108, v108, 7, v242
	global_load_dwordx4 v[116:119], v108, s[98:99]
	s_nop 0
	global_load_dwordx4 v[108:111], v108, s[98:99] offset:64
	s_waitcnt lgkmcnt(0)
	v_lshl_add_u32 v120, v120, 7, v242
	global_load_dwordx4 v[124:127], v120, s[98:99]
	s_nop 0
	global_load_dwordx4 v[120:123], v120, s[98:99] offset:64
	s_waitcnt vmcnt(31)
	v_mfma_f32_16x16x32_fp8_fp8 v[156:159], v[148:149], v[4:5], 0
	v_cmp_gt_u32_e32 vcc, s50, v189
	v_mfma_f32_16x16x32_fp8_fp8 v[4:7], v[150:151], v[6:7], v[156:159]
	s_waitcnt vmcnt(30)
	v_mfma_f32_16x16x32_fp8_fp8 v[4:7], v[152:153], v[0:1], v[4:7]
	v_mfma_f32_16x16x32_fp8_fp8 v[4:7], v[154:155], v[2:3], v[4:7]
	s_waitcnt vmcnt(29)
	v_mfma_f32_16x16x32_fp8_fp8 v[0:3], v[148:149], v[12:13], 0
	v_mfma_f32_16x16x32_fp8_fp8 v[0:3], v[150:151], v[14:15], v[0:3]
	s_waitcnt vmcnt(28)
	v_mfma_f32_16x16x32_fp8_fp8 v[0:3], v[152:153], v[8:9], v[0:3]
	v_mfma_f32_16x16x32_fp8_fp8 v[8:11], v[154:155], v[10:11], v[0:3]
	s_waitcnt vmcnt(27)
	v_mfma_f32_16x16x32_fp8_fp8 v[0:3], v[148:149], v[20:21], 0
	v_mfma_f32_16x16x32_fp8_fp8 v[0:3], v[150:151], v[22:23], v[0:3]
	s_waitcnt vmcnt(26)
	v_mfma_f32_16x16x32_fp8_fp8 v[0:3], v[152:153], v[16:17], v[0:3]
	v_mfma_f32_16x16x32_fp8_fp8 v[12:15], v[154:155], v[18:19], v[0:3]
	s_waitcnt vmcnt(25)
	v_mfma_f32_16x16x32_fp8_fp8 v[0:3], v[148:149], v[28:29], 0
	v_mfma_f32_16x16x32_fp8_fp8 v[0:3], v[150:151], v[30:31], v[0:3]
	s_waitcnt vmcnt(24)
	v_mfma_f32_16x16x32_fp8_fp8 v[0:3], v[152:153], v[24:25], v[0:3]
	v_mfma_f32_16x16x32_fp8_fp8 v[16:19], v[154:155], v[26:27], v[0:3]
	s_waitcnt vmcnt(23)
	v_mfma_f32_16x16x32_fp8_fp8 v[0:3], v[148:149], v[36:37], 0
	v_mfma_f32_16x16x32_fp8_fp8 v[0:3], v[150:151], v[38:39], v[0:3]
	s_waitcnt vmcnt(22)
	v_mfma_f32_16x16x32_fp8_fp8 v[0:3], v[152:153], v[32:33], v[0:3]
	v_mfma_f32_16x16x32_fp8_fp8 v[20:23], v[154:155], v[34:35], v[0:3]
	s_waitcnt vmcnt(21)
	v_mfma_f32_16x16x32_fp8_fp8 v[0:3], v[148:149], v[44:45], 0
	v_mfma_f32_16x16x32_fp8_fp8 v[0:3], v[150:151], v[46:47], v[0:3]
	s_waitcnt vmcnt(20)
	v_mfma_f32_16x16x32_fp8_fp8 v[0:3], v[152:153], v[40:41], v[0:3]
	v_mfma_f32_16x16x32_fp8_fp8 v[24:27], v[154:155], v[42:43], v[0:3]
	s_waitcnt vmcnt(19)
	v_mfma_f32_16x16x32_fp8_fp8 v[0:3], v[148:149], v[52:53], 0
	v_mfma_f32_16x16x32_fp8_fp8 v[0:3], v[150:151], v[54:55], v[0:3]
	s_waitcnt vmcnt(18)
	v_mfma_f32_16x16x32_fp8_fp8 v[0:3], v[152:153], v[48:49], v[0:3]
	v_mfma_f32_16x16x32_fp8_fp8 v[28:31], v[154:155], v[50:51], v[0:3]
	s_waitcnt vmcnt(17)
	v_mfma_f32_16x16x32_fp8_fp8 v[0:3], v[148:149], v[60:61], 0
	v_mfma_f32_16x16x32_fp8_fp8 v[0:3], v[150:151], v[62:63], v[0:3]
	s_waitcnt vmcnt(16)
	v_mfma_f32_16x16x32_fp8_fp8 v[0:3], v[152:153], v[56:57], v[0:3]
	v_mfma_f32_16x16x32_fp8_fp8 v[32:35], v[154:155], v[58:59], v[0:3]
	s_waitcnt vmcnt(15)
	v_mfma_f32_16x16x32_fp8_fp8 v[0:3], v[148:149], v[68:69], 0
	v_mfma_f32_16x16x32_fp8_fp8 v[0:3], v[150:151], v[70:71], v[0:3]
	s_waitcnt vmcnt(14)
	v_mfma_f32_16x16x32_fp8_fp8 v[0:3], v[152:153], v[64:65], v[0:3]
	v_mfma_f32_16x16x32_fp8_fp8 v[36:39], v[154:155], v[66:67], v[0:3]
	s_waitcnt vmcnt(13)
	v_mfma_f32_16x16x32_fp8_fp8 v[0:3], v[148:149], v[76:77], 0
	v_mfma_f32_16x16x32_fp8_fp8 v[0:3], v[150:151], v[78:79], v[0:3]
	s_waitcnt vmcnt(11)
	v_mfma_f32_16x16x32_fp8_fp8 v[44:47], v[148:149], v[88:89], 0
	s_waitcnt vmcnt(9)
	v_mfma_f32_16x16x32_fp8_fp8 v[48:51], v[148:149], v[96:97], 0
	v_mfma_f32_16x16x32_fp8_fp8 v[0:3], v[152:153], v[72:73], v[0:3]
	s_waitcnt vmcnt(7)
; __device__ __forceinline__ void dsa_attend(const h16* PROJ, const unsigned short* IDX, const int* CNT, h16* MIXA, unsigned char* shm, unsigned* bar, unsigned xcc, unsigned xrank) {
;     ...
;                 for (int e = 0; e < 16; ++e) {
;                     f32x4 a = (f32x4){0.f, 0.f, 0.f, 0.f};
; #pragma unroll
;                     for (int L = 0; L < 2; ++L) {
;                         const long k0 = (long)(((unsigned long long)kf[e][L].y << 32) | (unsigned long long)kf[e][L].x), k1 = (long)(((unsigned long long)kf[e][L].w << 32) | (unsigned long long)kf[e][L].z);
;                         a = __builtin_amdgcn_mfma_f32_16x16x32_fp8_fp8(qa8[2 * L], k0, a, 0, 0, 0); a = __builtin_amdgcn_mfma_f32_16x16x32_fp8_fp8(qa8[2 * L + 1], k1, a, 0, 0, 0); }
;                     if (16 * e + fr >= nsel) a = (f32x4){-1e30f, -1e30f, -1e30f, -1e30f};
;                     sacc[e] = a; }
;                 __builtin_amdgcn_sched_barrier(0);
;             }
;             f32x4 mx = sacc[0];
; #pragma unroll
;             for (int jt = 1; jt < 16; ++jt)
; #pragma unroll
;                 for (int i = 0; i < 4; ++i) mx[i] = fmaxf(mx[i], sacc[jt][i]);
; #pragma unroll
;             for (int o = 1; o < 16; o <<= 1)
; #pragma unroll
;                 for (int i = 0; i < 4; ++i) mx[i] = fmaxf(mx[i], __shfl_xor(mx[i], o));
	v_mfma_f32_16x16x32_fp8_fp8 v[52:55], v[148:149], v[104:105], 0
	s_waitcnt vmcnt(5)
	v_mfma_f32_16x16x32_fp8_fp8 v[56:59], v[148:149], v[112:113], 0
	v_mfma_f32_16x16x32_fp8_fp8 v[44:47], v[150:151], v[90:91], v[44:47]
	s_waitcnt vmcnt(3)
	v_mfma_f32_16x16x32_fp8_fp8 v[60:63], v[148:149], v[116:117], 0
	v_mfma_f32_16x16x32_fp8_fp8 v[48:51], v[150:151], v[98:99], v[48:51]
	v_mfma_f32_16x16x32_fp8_fp8 v[40:43], v[154:155], v[74:75], v[0:3]
	s_nop 2
	v_cndmask_b32_e32 v2, v219, v7, vcc
	v_cndmask_b32_e32 v3, v219, v6, vcc
	v_cndmask_b32_e32 v1, v219, v5, vcc
	v_cndmask_b32_e32 v0, v219, v4, vcc
	v_cmp_gt_u32_e32 vcc, s67, v194
	v_mfma_f32_16x16x32_fp8_fp8 v[52:55], v[150:151], v[106:107], v[52:55]
	s_nop 0
	v_cndmask_b32_e32 v7, v219, v11, vcc
	v_cndmask_b32_e32 v6, v219, v10, vcc
	v_cndmask_b32_e32 v9, v219, v9, vcc
	v_cndmask_b32_e32 v8, v219, v8, vcc
	v_cmp_gt_u32_e32 vcc, s67, v195
	v_mfma_f32_16x16x32_fp8_fp8 v[56:59], v[150:151], v[114:115], v[56:59]
	s_nop 0
	v_cndmask_b32_e32 v11, v219, v15, vcc
	v_cndmask_b32_e32 v10, v219, v14, vcc
	v_mfma_f32_16x16x32_fp8_fp8 v[44:47], v[152:153], v[80:81], v[44:47]
	v_cndmask_b32_e32 v69, v219, v13, vcc
	v_cndmask_b32_e32 v12, v219, v12, vcc
	v_cmp_gt_u32_e32 vcc, s67, v196
	v_mfma_f32_16x16x32_fp8_fp8 v[60:63], v[150:151], v[118:119], v[60:63]
	s_nop 0
	v_cndmask_b32_e32 v15, v219, v19, vcc
	v_cndmask_b32_e32 v14, v219, v18, vcc
	s_waitcnt vmcnt(1)
	v_mfma_f32_16x16x32_fp8_fp8 v[64:67], v[148:149], v[124:125], 0
	v_cndmask_b32_e32 v13, v219, v17, vcc
	v_cndmask_b32_e32 v70, v219, v16, vcc
	v_cmp_gt_u32_e32 vcc, s67, v197
	v_mfma_f32_16x16x32_fp8_fp8 v[48:51], v[152:153], v[84:85], v[48:51]
	s_nop 0
	v_cndmask_b32_e32 v19, v219, v23, vcc
	v_cndmask_b32_e32 v18, v219, v22, vcc
	v_cndmask_b32_e32 v17, v219, v21, vcc
	v_cndmask_b32_e32 v16, v219, v20, vcc
	v_cmp_gt_u32_e32 vcc, s67, v198
	v_mfma_f32_16x16x32_fp8_fp8 v[52:55], v[152:153], v[92:93], v[52:55]
	s_nop 0
	v_cndmask_b32_e32 v23, v219, v27, vcc
	v_cndmask_b32_e32 v22, v219, v26, vcc
	v_cndmask_b32_e32 v21, v219, v25, vcc
	v_cndmask_b32_e32 v20, v219, v24, vcc
	v_cmp_gt_u32_e32 vcc, s67, v199
	v_mfma_f32_16x16x32_fp8_fp8 v[56:59], v[152:153], v[100:101], v[56:59]
	s_nop 0
	v_cndmask_b32_e32 v27, v219, v31, vcc
	v_cndmask_b32_e32 v26, v219, v30, vcc
	v_mfma_f32_16x16x32_fp8_fp8 v[44:47], v[154:155], v[82:83], v[44:47]
	v_cndmask_b32_e32 v25, v219, v29, vcc
	v_cndmask_b32_e32 v24, v219, v28, vcc
	v_cmp_gt_u32_e32 vcc, s67, v200
	v_mfma_f32_16x16x32_fp8_fp8 v[60:63], v[152:153], v[108:109], v[60:63]
	s_nop 0
	v_cndmask_b32_e32 v31, v219, v35, vcc
	v_cndmask_b32_e32 v30, v219, v34, vcc
	v_mfma_f32_16x16x32_fp8_fp8 v[64:67], v[150:151], v[126:127], v[64:67]
	v_cndmask_b32_e32 v29, v219, v33, vcc
	v_cndmask_b32_e32 v28, v219, v32, vcc
	v_cmp_gt_u32_e32 vcc, s67, v201
	v_mfma_f32_16x16x32_fp8_fp8 v[48:51], v[154:155], v[86:87], v[48:51]
	s_nop 0
	v_cndmask_b32_e32 v35, v219, v39, vcc
	v_cndmask_b32_e32 v34, v219, v38, vcc
	v_mfma_f32_16x16x32_fp8_fp8 v[52:55], v[154:155], v[94:95], v[52:55]
	v_cndmask_b32_e32 v33, v219, v37, vcc
	v_cndmask_b32_e32 v32, v219, v36, vcc
	v_cmp_gt_u32_e32 vcc, s67, v202
	v_mfma_f32_16x16x32_fp8_fp8 v[56:59], v[154:155], v[102:103], v[56:59]
	s_nop 0
	v_cndmask_b32_e32 v39, v219, v43, vcc
	v_cndmask_b32_e32 v38, v219, v42, vcc
	v_cndmask_b32_e32 v37, v219, v41, vcc
	v_cndmask_b32_e32 v36, v219, v40, vcc
	v_cmp_gt_u32_e32 vcc, s67, v203
	v_mfma_f32_16x16x32_fp8_fp8 v[60:63], v[154:155], v[110:111], v[60:63]
	s_nop 0
	v_cndmask_b32_e32 v43, v219, v47, vcc
	v_cndmask_b32_e32 v42, v219, v46, vcc
	v_cndmask_b32_e32 v41, v219, v45, vcc
	v_cndmask_b32_e32 v40, v219, v44, vcc
	v_cmp_gt_u32_e32 vcc, s67, v204
	s_waitcnt vmcnt(0)
	v_mfma_f32_16x16x32_fp8_fp8 v[64:67], v[152:153], v[120:121], v[64:67]
	v_cndmask_b32_e32 v47, v219, v51, vcc
	v_cndmask_b32_e32 v46, v219, v50, vcc
	v_cndmask_b32_e32 v45, v219, v49, vcc
	v_cndmask_b32_e32 v44, v219, v48, vcc
	v_cmp_gt_u32_e32 vcc, s67, v205
	s_nop 1
	v_cndmask_b32_e32 v51, v219, v55, vcc
	v_cndmask_b32_e32 v50, v219, v54, vcc
	v_cndmask_b32_e32 v49, v219, v53, vcc
	v_cndmask_b32_e32 v48, v219, v52, vcc
	v_cmp_gt_u32_e32 vcc, s67, v206
	s_nop 1
	v_cndmask_b32_e32 v55, v219, v59, vcc
	v_cndmask_b32_e32 v54, v219, v58, vcc
	v_cndmask_b32_e32 v53, v219, v57, vcc
	v_cndmask_b32_e32 v52, v219, v56, vcc
	v_cmp_gt_u32_e32 vcc, s67, v207
	s_nop 1
	v_cndmask_b32_e32 v59, v219, v63, vcc
	v_cndmask_b32_e32 v58, v219, v62, vcc
	v_cndmask_b32_e32 v57, v219, v61, vcc
	v_cndmask_b32_e32 v56, v219, v60, vcc
	v_mfma_f32_16x16x32_fp8_fp8 v[60:63], v[154:155], v[122:123], v[64:67]
	v_cmp_gt_u32_e32 vcc, s67, v208
	s_nop 6
	v_cndmask_b32_e32 v63, v219, v63, vcc
	v_cndmask_b32_e32 v62, v219, v62, vcc
	v_cndmask_b32_e32 v61, v219, v61, vcc
	v_cndmask_b32_e32 v60, v219, v60, vcc
	v_max_f32_e32 v4, v8, v8
	v_max_f32_e32 v5, v0, v0
	v_max_f32_e32 v4, v5, v4
	v_max_f32_e32 v5, v9, v9
	v_max_f32_e32 v64, v1, v1
	v_max_f32_e32 v5, v64, v5
	v_max_f32_e32 v64, v6, v6
	v_max_f32_e32 v65, v3, v3
	v_max3_f32 v4, v4, v12, v70
	v_max_f32_e32 v64, v65, v64
	v_max_f32_e32 v65, v7, v7
	v_max_f32_e32 v66, v2, v2
	v_max3_f32 v4, v4, v16, v20
	v_max_f32_e32 v65, v66, v65
	v_max3_f32 v4, v4, v24, v28
	v_and_b32_e32 v66, 64, v216
	v_max3_f32 v4, v4, v32, v36
	v_add_u32_e32 v224, 64, v66
	v_xor_b32_e32 v66, 1, v216
	v_max3_f32 v4, v4, v40, v44
	v_cmp_lt_i32_e32 vcc, v66, v224
	v_max3_f32 v4, v4, v48, v52
	v_max3_f32 v5, v5, v69, v13
	v_cndmask_b32_e32 v66, v216, v66, vcc
	v_max3_f32 v4, v4, v56, v60
	v_lshlrev_b32_e32 v66, 2, v66
	v_max3_f32 v5, v5, v17, v21
	ds_bpermute_b32 v67, v66, v4
	v_max3_f32 v5, v5, v25, v29
	v_max3_f32 v5, v5, v33, v37
	v_max3_f32 v5, v5, v41, v45
	v_max3_f32 v5, v5, v49, v53
	v_max3_f32 v64, v64, v10, v14
	v_max3_f32 v5, v5, v57, v61
	s_waitcnt lgkmcnt(0)
; __device__ __forceinline__ void dsa_attend(const h16* PROJ, const unsigned short* IDX, const int* CNT, h16* MIXA, unsigned char* shm, unsigned* bar, unsigned xcc, unsigned xrank) {
;     ...
;             f32x4 mx = sacc[0];
; #pragma unroll
;             for (int jt = 1; jt < 16; ++jt)
; #pragma unroll
;                 for (int i = 0; i < 4; ++i) mx[i] = fmaxf(mx[i], sacc[jt][i]);
; #pragma unroll
;             for (int o = 1; o < 16; o <<= 1)
; #pragma unroll
;                 for (int i = 0; i < 4; ++i) mx[i] = fmaxf(mx[i], __shfl_xor(mx[i], o));
;             f32x4 sm = (f32x4){0.f, 0.f, 0.f, 0.f};
;             const float sc = 0.08838834764831845f;
; #pragma unroll
;             for (int jt = 0; jt < 16; ++jt)
; #pragma unroll
;                 for (int i = 0; i < 4; ++i) { const float e = __expf((sacc[jt][i] - mx[i]) * sc); sacc[jt][i] = e; sm[i] += e; }
	v_max_f32_e32 v67, v67, v67
	v_max3_f32 v64, v64, v18, v22
	v_max_f32_e32 v4, v4, v67
	ds_bpermute_b32 v67, v66, v5
	v_max3_f32 v64, v64, v26, v30
	v_max3_f32 v64, v64, v34, v38
	v_max3_f32 v64, v64, v42, v46
	v_max3_f32 v64, v64, v50, v54
	v_max3_f32 v65, v65, v11, v15
	v_max3_f32 v64, v64, v58, v62
	s_waitcnt lgkmcnt(0)
	v_max_f32_e32 v67, v67, v67
	v_max3_f32 v65, v65, v19, v23
	v_max_f32_e32 v5, v5, v67
	ds_bpermute_b32 v67, v66, v64
	v_max3_f32 v65, v65, v27, v31
	v_max3_f32 v65, v65, v35, v39
	v_max3_f32 v65, v65, v43, v47
	v_max3_f32 v65, v65, v51, v55
	v_max3_f32 v65, v65, v59, v63
	s_waitcnt lgkmcnt(0)
	v_max_f32_e32 v67, v67, v67
	v_max_f32_e32 v64, v64, v67
	ds_bpermute_b32 v67, v66, v65
	s_waitcnt lgkmcnt(0)
	v_max_f32_e32 v67, v67, v67
	v_max_f32_e32 v65, v65, v67
	v_xor_b32_e32 v67, 2, v216
	v_cmp_lt_i32_e32 vcc, v67, v224
	s_nop 1
	v_cndmask_b32_e32 v67, v216, v67, vcc
	v_lshlrev_b32_e32 v67, 2, v67
	ds_bpermute_b32 v68, v67, v4
	s_waitcnt lgkmcnt(0)
	v_max_f32_e32 v68, v68, v68
	v_max_f32_e32 v4, v4, v68
	ds_bpermute_b32 v68, v67, v5
	s_waitcnt lgkmcnt(0)
	v_max_f32_e32 v68, v68, v68
	v_max_f32_e32 v5, v5, v68
	ds_bpermute_b32 v68, v67, v64
	s_waitcnt lgkmcnt(0)
	v_max_f32_e32 v68, v68, v68
	v_max_f32_e32 v64, v64, v68
	ds_bpermute_b32 v68, v67, v65
	s_waitcnt lgkmcnt(0)
	v_max_f32_e32 v68, v68, v68
	v_max_f32_e32 v65, v65, v68
	v_xor_b32_e32 v68, 4, v216
	v_cmp_lt_i32_e32 vcc, v68, v224
	s_nop 1
	v_cndmask_b32_e32 v68, v216, v68, vcc
	v_lshlrev_b32_e32 v68, 2, v68
	ds_bpermute_b32 v71, v68, v4
	s_waitcnt lgkmcnt(0)
	v_max_f32_e32 v71, v71, v71
	v_max_f32_e32 v4, v4, v71
	ds_bpermute_b32 v71, v68, v5
	s_waitcnt lgkmcnt(0)
	v_max_f32_e32 v71, v71, v71
	v_max_f32_e32 v5, v5, v71
	ds_bpermute_b32 v71, v68, v64
	s_waitcnt lgkmcnt(0)
	v_max_f32_e32 v71, v71, v71
	v_max_f32_e32 v64, v64, v71
	ds_bpermute_b32 v71, v68, v65
	s_waitcnt lgkmcnt(0)
	v_max_f32_e32 v71, v71, v71
	v_max_f32_e32 v65, v65, v71
	v_xor_b32_e32 v71, 8, v216
	v_cmp_lt_i32_e32 vcc, v71, v224
	s_nop 1
	v_cndmask_b32_e32 v71, v216, v71, vcc
	v_lshlrev_b32_e32 v223, 2, v71
	ds_bpermute_b32 v71, v223, v4
	s_waitcnt lgkmcnt(0)
	v_max_f32_e32 v71, v71, v71
	v_max_f32_e32 v72, v4, v71
	ds_bpermute_b32 v4, v223, v5
	v_mul_f32_e32 v236, 0xbe0293ee, v72
	v_fma_f32 v0, v0, v244, v236
	v_exp_f32_e32 v0, v0
	s_waitcnt lgkmcnt(0)
	v_max_f32_e32 v4, v4, v4
	v_max_f32_e32 v73, v5, v4
	ds_bpermute_b32 v4, v223, v64
	v_mul_f32_e32 v237, 0xbe0293ee, v73
	v_fma_f32 v1, v1, v244, v237
	v_exp_f32_e32 v1, v1
	s_waitcnt lgkmcnt(0)
	v_max_f32_e32 v4, v4, v4
	v_max_f32_e32 v74, v64, v4
	ds_bpermute_b32 v4, v223, v65
	v_mul_f32_e32 v238, 0xbe0293ee, v74
	v_fma_f32 v3, v3, v244, v238
	v_fma_f32 v13, v13, v244, v237
	s_waitcnt lgkmcnt(0)
	v_max_f32_e32 v4, v4, v4
	v_max_f32_e32 v75, v65, v4
	v_mul_f32_e32 v239, 0xbe0293ee, v75
	v_fma_f32 v2, v2, v244, v239
	v_exp_f32_e32 v4, v3
	v_exp_f32_e32 v5, v2
	v_fma_f32 v2, v8, v244, v236
	v_fma_f32 v3, v9, v244, v237
	v_fma_f32 v8, v12, v244, v236
	v_fma_f32 v9, v69, v244, v237
	v_fma_f32 v12, v70, v244, v236
	v_exp_f32_e32 v2, v2
	v_exp_f32_e32 v3, v3
	v_fma_f32 v16, v16, v244, v236
	v_fma_f32 v17, v17, v244, v237
	v_exp_f32_e32 v8, v8
	v_exp_f32_e32 v9, v9
	v_fma_f32 v20, v20, v244, v236
	v_fma_f32 v21, v21, v244, v237
	v_exp_f32_e32 v12, v12
	v_exp_f32_e32 v13, v13
	v_fma_f32 v24, v24, v244, v236
	v_fma_f32 v25, v25, v244, v237
	v_exp_f32_e32 v16, v16
	v_exp_f32_e32 v17, v17
	v_fma_f32 v28, v28, v244, v236
	v_fma_f32 v29, v29, v244, v237
	v_pk_add_f32 v[64:65], v[0:1], 0 op_sel_hi:[1,0]
	v_exp_f32_e32 v20, v20
	v_exp_f32_e32 v21, v21
	v_fma_f32 v32, v32, v244, v236
	v_fma_f32 v33, v33, v244, v237
	v_pk_add_f32 v[64:65], v[2:3], v[64:65]
	v_exp_f32_e32 v24, v24
	v_exp_f32_e32 v25, v25
	v_fma_f32 v36, v36, v244, v236
	v_fma_f32 v37, v37, v244, v237
	v_pk_add_f32 v[64:65], v[8:9], v[64:65]
	v_exp_f32_e32 v28, v28
	v_exp_f32_e32 v29, v29
	v_pk_add_f32 v[64:65], v[12:13], v[64:65]
	v_fma_f32 v40, v40, v244, v236
	v_fma_f32 v41, v41, v244, v237
	v_exp_f32_e32 v32, v32
	v_exp_f32_e32 v33, v33
	v_pk_add_f32 v[64:65], v[16:17], v[64:65]
	v_fma_f32 v44, v44, v244, v236
	v_fma_f32 v45, v45, v244, v237
	v_exp_f32_e32 v36, v36
	v_exp_f32_e32 v37, v37
	v_pk_add_f32 v[64:65], v[20:21], v[64:65]
	v_fma_f32 v48, v48, v244, v236
	v_fma_f32 v49, v49, v244, v237
	v_pk_add_f32 v[64:65], v[24:25], v[64:65]
	v_exp_f32_e32 v40, v40
	v_exp_f32_e32 v41, v41
	v_fma_f32 v52, v52, v244, v236
	v_fma_f32 v53, v53, v244, v237
	v_pk_add_f32 v[64:65], v[28:29], v[64:65]
	v_exp_f32_e32 v44, v44
	v_exp_f32_e32 v45, v45
	v_fma_f32 v56, v56, v244, v236
	v_fma_f32 v57, v57, v244, v237
	v_pk_add_f32 v[64:65], v[32:33], v[64:65]
	v_exp_f32_e32 v48, v48
	v_exp_f32_e32 v49, v49
	v_fma_f32 v60, v60, v244, v236
	v_fma_f32 v61, v61, v244, v237
	v_pk_add_f32 v[64:65], v[36:37], v[64:65]
	v_exp_f32_e32 v52, v52
	v_exp_f32_e32 v53, v53
	v_exp_f32_e32 v56, v56
	v_exp_f32_e32 v57, v57
	v_pk_add_f32 v[64:65], v[40:41], v[64:65]
	v_fma_f32 v6, v6, v244, v238
	v_fma_f32 v7, v7, v244, v239
	v_exp_f32_e32 v60, v60
	v_exp_f32_e32 v61, v61
	v_pk_add_f32 v[64:65], v[44:45], v[64:65]
	v_fma_f32 v10, v10, v244, v238
	v_fma_f32 v11, v11, v244, v239
	v_pk_add_f32 v[64:65], v[48:49], v[64:65]
	v_fma_f32 v14, v14, v244, v238
	v_fma_f32 v15, v15, v244, v239
	v_pk_add_f32 v[64:65], v[52:53], v[64:65]
	v_exp_f32_e32 v6, v6
	v_exp_f32_e32 v7, v7
	v_fma_f32 v18, v18, v244, v238
	v_fma_f32 v19, v19, v244, v239
	v_pk_add_f32 v[64:65], v[56:57], v[64:65]
	v_exp_f32_e32 v10, v10
	v_exp_f32_e32 v11, v11
	v_fma_f32 v22, v22, v244, v238
	v_fma_f32 v23, v23, v244, v239
	v_pk_add_f32 v[64:65], v[60:61], v[64:65]
	v_exp_f32_e32 v14, v14
	v_exp_f32_e32 v15, v15
	v_fma_f32 v26, v26, v244, v238
	v_fma_f32 v27, v27, v244, v239
	ds_bpermute_b32 v72, v66, v64
	ds_bpermute_b32 v73, v66, v65
	v_exp_f32_e32 v18, v18
	v_exp_f32_e32 v19, v19
	v_fma_f32 v30, v30, v244, v238
	v_fma_f32 v31, v31, v244, v239
	v_pk_add_f32 v[70:71], v[4:5], 0 op_sel_hi:[1,0]
	v_exp_f32_e32 v22, v22
	v_exp_f32_e32 v23, v23
	v_fma_f32 v34, v34, v244, v238
	v_fma_f32 v35, v35, v244, v239
	v_pk_add_f32 v[70:71], v[6:7], v[70:71]
	v_exp_f32_e32 v26, v26
	v_exp_f32_e32 v27, v27
	v_fma_f32 v38, v38, v244, v238
	v_fma_f32 v39, v39, v244, v239
	v_pk_add_f32 v[70:71], v[10:11], v[70:71]
	v_exp_f32_e32 v30, v30
	v_exp_f32_e32 v31, v31
	v_pk_add_f32 v[70:71], v[14:15], v[70:71]
	v_fma_f32 v42, v42, v244, v238
	v_fma_f32 v43, v43, v244, v239
	v_exp_f32_e32 v34, v34
	v_exp_f32_e32 v35, v35
	v_pk_add_f32 v[70:71], v[18:19], v[70:71]
	v_fma_f32 v46, v46, v244, v238
	v_fma_f32 v47, v47, v244, v239
	s_waitcnt lgkmcnt(0)
; __device__ __forceinline__ void dsa_attend(const h16* PROJ, const unsigned short* IDX, const int* CNT, h16* MIXA, unsigned char* shm, unsigned* bar, unsigned xcc, unsigned xrank) {
;     ...
;                 for (int i = 0; i < 4; ++i) { const float e = __expf((sacc[jt][i] - mx[i]) * sc); sacc[jt][i] = e; sm[i] += e; }
; #pragma unroll
;             for (int o = 1; o < 16; o <<= 1)
; #pragma unroll
;                 for (int i = 0; i < 4; ++i) sm[i] += __shfl_xor(sm[i], o);
;             f32x4 inv;
; #pragma unroll
;             for (int i = 0; i < 4; ++i) inv[i] = 1.f / sm[i];
;             if (fq == 0) {
; #pragma unroll
;                 for (int jt = 0; jt < 16; ++jt) *(f32x4*)(Pl + ((size_t)wid * 256 + 16 * jt + fr) * 4) = sacc[jt] * inv;
;             }
	v_pk_add_f32 v[64:65], v[64:65], v[72:73]
	v_exp_f32_e32 v38, v38
	v_exp_f32_e32 v39, v39
	v_pk_add_f32 v[70:71], v[22:23], v[70:71]
	v_fma_f32 v50, v50, v244, v238
	v_fma_f32 v51, v51, v244, v239
	ds_bpermute_b32 v72, v67, v64
	ds_bpermute_b32 v73, v67, v65
	v_pk_add_f32 v[70:71], v[26:27], v[70:71]
	v_exp_f32_e32 v42, v42
	v_exp_f32_e32 v43, v43
	v_fma_f32 v54, v54, v244, v238
	v_fma_f32 v55, v55, v244, v239
	v_pk_add_f32 v[70:71], v[30:31], v[70:71]
	v_exp_f32_e32 v46, v46
	v_exp_f32_e32 v47, v47
	v_fma_f32 v58, v58, v244, v238
	v_fma_f32 v59, v59, v244, v239
	v_pk_add_f32 v[70:71], v[34:35], v[70:71]
	v_exp_f32_e32 v50, v50
	v_exp_f32_e32 v51, v51
	v_fma_f32 v62, v62, v244, v238
	v_fma_f32 v63, v63, v244, v239
	v_pk_add_f32 v[70:71], v[38:39], v[70:71]
	v_exp_f32_e32 v54, v54
	v_exp_f32_e32 v55, v55
	v_exp_f32_e32 v58, v58
	v_exp_f32_e32 v59, v59
	s_waitcnt lgkmcnt(0)
	v_pk_add_f32 v[64:65], v[64:65], v[72:73]
	v_pk_add_f32 v[70:71], v[42:43], v[70:71]
	v_exp_f32_e32 v62, v62
	v_exp_f32_e32 v63, v63
	ds_bpermute_b32 v72, v68, v64
	ds_bpermute_b32 v73, v68, v65
	v_pk_add_f32 v[70:71], v[46:47], v[70:71]
	s_waitcnt lgkmcnt(0)
	v_pk_add_f32 v[64:65], v[64:65], v[72:73]
	v_pk_add_f32 v[70:71], v[50:51], v[70:71]
	s_nop 0
	v_pk_add_f32 v[70:71], v[54:55], v[70:71]
	s_nop 0
	v_pk_add_f32 v[70:71], v[58:59], v[70:71]
	s_nop 0
	v_pk_add_f32 v[70:71], v[62:63], v[70:71]
	ds_bpermute_b32 v72, v66, v70
	ds_bpermute_b32 v73, v66, v71
	s_waitcnt lgkmcnt(0)
	v_pk_add_f32 v[70:71], v[70:71], v[72:73]
	ds_bpermute_b32 v66, v67, v70
	ds_bpermute_b32 v67, v67, v71
	s_waitcnt lgkmcnt(0)
	v_pk_add_f32 v[66:67], v[70:71], v[66:67]
	ds_bpermute_b32 v70, v68, v66
	ds_bpermute_b32 v71, v68, v67
	s_waitcnt lgkmcnt(0)
	v_pk_add_f32 v[68:69], v[66:67], v[70:71]
	ds_bpermute_b32 v66, v223, v64
	ds_bpermute_b32 v67, v223, v65
	ds_bpermute_b32 v70, v223, v68
	ds_bpermute_b32 v71, v223, v69
	s_and_saveexec_b64 s[50:51], s[46:47]
	s_cbranch_execz .LBB0_848
	s_waitcnt lgkmcnt(2)
	v_pk_add_f32 v[64:65], v[64:65], v[66:67]
	s_waitcnt lgkmcnt(0)
	v_pk_add_f32 v[68:69], v[68:69], v[70:71]
	v_div_scale_f32 v66, s[60:61], v65, v65, 1.0
	v_rcp_f32_e32 v67, v66
	s_nop 0
	v_fma_f32 v70, -v66, v67, 1.0
	v_fmac_f32_e32 v67, v70, v67
	v_div_scale_f32 v70, vcc, 1.0, v65, 1.0
	v_mul_f32_e32 v71, v70, v67
	v_fma_f32 v72, -v66, v71, v70
	v_fmac_f32_e32 v71, v72, v67
	v_fma_f32 v66, -v66, v71, v70
	v_div_fmas_f32 v66, v66, v67, v71
	v_div_fixup_f32 v71, v66, v65, 1.0
	v_div_scale_f32 v65, s[60:61], v64, v64, 1.0
	v_rcp_f32_e32 v66, v65
	s_nop 0
	v_fma_f32 v67, -v65, v66, 1.0
	v_fmac_f32_e32 v66, v67, v66
	v_div_scale_f32 v67, vcc, 1.0, v64, 1.0
	v_mul_f32_e32 v70, v67, v66
	v_fma_f32 v72, -v65, v70, v67
	v_fmac_f32_e32 v70, v72, v66
	v_fma_f32 v65, -v65, v70, v67
	v_div_fmas_f32 v65, v65, v66, v70
	v_div_fixup_f32 v70, v65, v64, 1.0
	v_div_scale_f32 v64, s[60:61], v69, v69, 1.0
	v_rcp_f32_e32 v65, v64
	v_pk_mul_f32 v[2:3], v[2:3], v[70:71]
	v_fma_f32 v66, -v64, v65, 1.0
	v_fmac_f32_e32 v65, v66, v65
	v_div_scale_f32 v66, vcc, 1.0, v69, 1.0
	v_mul_f32_e32 v67, v66, v65
	v_fma_f32 v72, -v64, v67, v66
	v_fmac_f32_e32 v67, v72, v65
	v_fma_f32 v64, -v64, v67, v66
	v_div_fmas_f32 v64, v64, v65, v67
	v_div_fixup_f32 v69, v64, v69, 1.0
	v_div_scale_f32 v64, s[60:61], v68, v68, 1.0
	v_rcp_f32_e32 v65, v64
	s_nop 0
	v_fma_f32 v66, -v64, v65, 1.0
	v_fmac_f32_e32 v65, v66, v65
	v_div_scale_f32 v66, vcc, 1.0, v68, 1.0
	v_mul_f32_e32 v67, v66, v65
	v_fma_f32 v72, -v64, v67, v66
	v_fmac_f32_e32 v67, v72, v65
	v_fma_f32 v64, -v64, v67, v66
	v_div_fmas_f32 v64, v64, v65, v67
	v_div_fixup_f32 v68, v64, v68, 1.0
	v_pk_mul_f32 v[66:67], v[4:5], v[68:69]
	v_pk_mul_f32 v[4:5], v[6:7], v[68:69]
	v_pk_mul_f32 v[64:65], v[0:1], v[70:71]
	ds_write_b128 v210, v[2:5] offset:256
	v_pk_mul_f32 v[2:3], v[10:11], v[68:69]
	v_pk_mul_f32 v[0:1], v[8:9], v[70:71]
	ds_write_b128 v210, v[0:3] offset:512
	v_pk_mul_f32 v[2:3], v[14:15], v[68:69]
	v_pk_mul_f32 v[0:1], v[12:13], v[70:71]
	ds_write_b128 v210, v[0:3] offset:768
	v_pk_mul_f32 v[2:3], v[18:19], v[68:69]
	v_pk_mul_f32 v[0:1], v[16:17], v[70:71]
	ds_write_b128 v210, v[0:3] offset:1024
	v_pk_mul_f32 v[2:3], v[22:23], v[68:69]
	v_pk_mul_f32 v[0:1], v[20:21], v[70:71]
	ds_write_b128 v210, v[0:3] offset:1280
	v_pk_mul_f32 v[2:3], v[26:27], v[68:69]
	v_pk_mul_f32 v[0:1], v[24:25], v[70:71]
	ds_write_b128 v210, v[0:3] offset:1536
	v_pk_mul_f32 v[2:3], v[30:31], v[68:69]
	v_pk_mul_f32 v[0:1], v[28:29], v[70:71]
	ds_write_b128 v210, v[0:3] offset:1792
	v_pk_mul_f32 v[2:3], v[34:35], v[68:69]
	v_pk_mul_f32 v[0:1], v[32:33], v[70:71]
	ds_write_b128 v210, v[0:3] offset:2048
	v_pk_mul_f32 v[2:3], v[38:39], v[68:69]
	v_pk_mul_f32 v[0:1], v[36:37], v[70:71]
	ds_write_b128 v210, v[0:3] offset:2304
	v_pk_mul_f32 v[2:3], v[42:43], v[68:69]
	v_pk_mul_f32 v[0:1], v[40:41], v[70:71]
	ds_write_b128 v210, v[0:3] offset:2560
	v_pk_mul_f32 v[2:3], v[46:47], v[68:69]
	v_pk_mul_f32 v[0:1], v[44:45], v[70:71]
	ds_write_b128 v210, v[0:3] offset:2816
	v_pk_mul_f32 v[2:3], v[50:51], v[68:69]
	v_pk_mul_f32 v[0:1], v[48:49], v[70:71]
	ds_write_b128 v210, v[0:3] offset:3072
	v_pk_mul_f32 v[2:3], v[54:55], v[68:69]
	v_pk_mul_f32 v[0:1], v[52:53], v[70:71]
	ds_write_b128 v210, v[0:3] offset:3328
	v_pk_mul_f32 v[2:3], v[58:59], v[68:69]
	v_pk_mul_f32 v[0:1], v[56:57], v[70:71]
	ds_write_b128 v210, v[0:3] offset:3584
	v_pk_mul_f32 v[2:3], v[62:63], v[68:69]
	v_pk_mul_f32 v[0:1], v[60:61], v[70:71]
	ds_write_b128 v210, v[64:67]
	ds_write_b128 v210, v[0:3] offset:3840

; __device__ __forceinline__ void dsa_attend(const h16* PROJ, const unsigned short* IDX, const int* CNT, h16* MIXA, unsigned char* shm, unsigned* bar, unsigned xcc, unsigned xrank) {
;     ...
;             for (int s0 = 0; s0 < nsel; s0 += 128) {
;                 uint4 vv[16];
; #pragma unroll
;                 for (int e = 0; e < 16; ++e) { const int slot = s0 + 8 * e + r8; const int idx = (int)sel[qq * 256 + (slot < nsel ? slot : nsel - 1)];
;                     vv[e] = *(const uint4*)(vbase8 + (size_t)idx * 128); }
;                 __builtin_amdgcn_sched_barrier(0);
; #pragma unroll
;                 for (int e = 0; e < 16; ++e) { const int slot = s0 + 8 * e + r8;
;                     if ((e & 3) == 0) __builtin_amdgcn_sched_barrier(0);
;                     const f32x4 pp = *(const f32x4*)(Pl + ((size_t)wid * 256 + slot) * 4);
;                     const f32x2 p0 = (f32x2){pp.x, pp.x}, p1 = (f32x2){pp.y, pp.y}, p2 = (f32x2){pp.z, pp.z}, p3 = (f32x2){pp.w, pp.w};
;                     const unsigned wds[4] = {vv[e].x, vv[e].y, vv[e].z, vv[e].w};
.LBB0_849:
	v_lshl_add_u32 v4, s50, 1, v241
	ds_read_u16 v0, v4 offset:32768
	ds_read_u16 v9, v4 offset:32784
	ds_read_u16 v10, v4 offset:32800
	ds_read_u16 v11, v4 offset:32816
	ds_read_u16 v5, v4 offset:32832
	ds_read_u16 v6, v4 offset:32848
	ds_read_u16 v7, v4 offset:32864
	ds_read_u16 v8, v4 offset:32880
	s_waitcnt lgkmcnt(7)
	v_lshl_add_u32 v0, v0, 7, v243
	s_waitcnt lgkmcnt(6)
	v_lshl_add_u32 v2, v9, 7, v243
	s_waitcnt lgkmcnt(5)
	global_load_dwordx4 v[226:229], v0, s[98:99]
	global_load_dwordx4 v[56:59], v2, s[98:99]
	v_lshl_add_u32 v0, v10, 7, v243
	s_waitcnt lgkmcnt(4)
	v_lshl_add_u32 v2, v11, 7, v243
	s_waitcnt lgkmcnt(3)
	global_load_dwordx4 v[52:55], v0, s[98:99]
	global_load_dwordx4 v[48:51], v2, s[98:99]
	v_lshl_add_u32 v0, v5, 7, v243
	s_waitcnt lgkmcnt(2)
	v_lshl_add_u32 v2, v6, 7, v243
	s_waitcnt lgkmcnt(1)
	global_load_dwordx4 v[44:47], v0, s[98:99]
	global_load_dwordx4 v[40:43], v2, s[98:99]
	v_lshl_add_u32 v0, v7, 7, v243
	s_waitcnt lgkmcnt(0)
	v_lshl_add_u32 v2, v8, 7, v243
	global_load_dwordx4 v[36:39], v0, s[98:99]
	global_load_dwordx4 v[28:31], v2, s[98:99]
	ds_read_u16 v0, v4 offset:32896
	ds_read_u16 v8, v4 offset:32912
	ds_read_u16 v9, v4 offset:32928
	ds_read_u16 v10, v4 offset:32944
	ds_read_u16 v5, v4 offset:32960
	ds_read_u16 v6, v4 offset:32976
	ds_read_u16 v7, v4 offset:32992
	ds_read_u16 v4, v4 offset:33008
	s_waitcnt lgkmcnt(7)
	v_lshl_add_u32 v0, v0, 7, v243
	s_waitcnt lgkmcnt(6)
	v_lshl_add_u32 v2, v8, 7, v243
	s_waitcnt lgkmcnt(5)
	global_load_dwordx4 v[32:35], v0, s[98:99]
	global_load_dwordx4 v[24:27], v2, s[98:99]
	v_lshl_add_u32 v0, v9, 7, v243
	s_waitcnt lgkmcnt(4)
	v_lshl_add_u32 v2, v10, 7, v243
	s_waitcnt lgkmcnt(3)
	global_load_dwordx4 v[20:23], v0, s[98:99]
	global_load_dwordx4 v[16:19], v2, s[98:99]
	v_lshl_add_u32 v0, v5, 7, v243
	s_waitcnt lgkmcnt(2)
	v_lshl_add_u32 v2, v6, 7, v243
	s_waitcnt lgkmcnt(1)
	global_load_dwordx4 v[12:15], v0, s[98:99]
	global_load_dwordx4 v[8:11], v2, s[98:99]
	v_lshl_add_u32 v0, v7, 7, v243
	s_waitcnt lgkmcnt(0)
	v_lshl_add_u32 v2, v4, 7, v243
	global_load_dwordx4 v[4:7], v0, s[98:99]
	s_nop 0
	global_load_dwordx4 v[0:3], v2, s[98:99]
	ds_read_b128 v[230:233], v225
	s_waitcnt vmcnt(15)
	v_cvt_pk_f32_fp8_e32 v[124:125], v226
	v_cvt_pk_f32_fp8_sdwa v[126:127], v226 src0_sel:WORD_1
	s_waitcnt lgkmcnt(0)
	v_mov_b32_e32 v162, v233
	v_pk_fma_f32 v[184:185], v[124:125], v[162:163], v[68:69] op_sel_hi:[1,0,1]
	v_pk_fma_f32 v[186:187], v[126:127], v[162:163], v[60:61] op_sel_hi:[1,0,1]
	v_cvt_pk_f32_fp8_e32 v[60:61], v227
	v_cvt_pk_f32_fp8_sdwa v[68:69], v227 src0_sel:WORD_1
	v_pk_fma_f32 v[148:149], v[124:125], v[230:231], v[110:111] op_sel_hi:[1,0,1]
	v_pk_fma_f32 v[150:151], v[126:127], v[230:231], v[112:113] op_sel_hi:[1,0,1]
	v_pk_fma_f32 v[152:153], v[124:125], v[230:231], v[104:105] op_sel:[0,1,0]
	v_pk_fma_f32 v[154:155], v[126:127], v[230:231], v[92:93] op_sel:[0,1,0]
	v_pk_fma_f32 v[156:157], v[124:125], v[232:233], v[86:87] op_sel_hi:[1,0,1]
	v_pk_fma_f32 v[158:159], v[126:127], v[232:233], v[76:77] op_sel_hi:[1,0,1]
	v_pk_fma_f32 v[104:105], v[60:61], v[230:231], v[118:119] op_sel_hi:[1,0,1]
	v_pk_fma_f32 v[110:111], v[68:69], v[230:231], v[116:117] op_sel_hi:[1,0,1]
	v_pk_fma_f32 v[98:99], v[60:61], v[230:231], v[98:99] op_sel:[0,1,0]
	v_pk_fma_f32 v[116:117], v[60:61], v[232:233], v[90:91] op_sel_hi:[1,0,1]
	v_pk_fma_f32 v[124:125], v[60:61], v[162:163], v[72:73] op_sel_hi:[1,0,1]
	v_pk_fma_f32 v[126:127], v[68:69], v[162:163], v[62:63] op_sel_hi:[1,0,1]
	v_cvt_pk_f32_fp8_e32 v[60:61], v228
	v_cvt_pk_f32_fp8_sdwa v[62:63], v228 src0_sel:WORD_1
	v_pk_fma_f32 v[112:113], v[68:69], v[230:231], v[96:97] op_sel:[0,1,0]
	v_pk_fma_f32 v[118:119], v[68:69], v[232:233], v[78:79] op_sel_hi:[1,0,1]
	v_pk_fma_f32 v[86:87], v[60:61], v[230:231], v[102:103] op_sel:[0,1,0]
	v_pk_fma_f32 v[90:91], v[62:63], v[230:231], v[100:101] op_sel:[0,1,0]
	v_cvt_pk_f32_fp8_e32 v[100:101], v229
	v_cvt_pk_f32_fp8_sdwa v[102:103], v229 src0_sel:WORD_1
	v_pk_fma_f32 v[76:77], v[60:61], v[230:231], v[120:121] op_sel_hi:[1,0,1]
	v_pk_fma_f32 v[78:79], v[62:63], v[230:231], v[108:109] op_sel_hi:[1,0,1]
	v_pk_fma_f32 v[82:83], v[60:61], v[232:233], v[82:83] op_sel_hi:[1,0,1]
	v_pk_fma_f32 v[80:81], v[62:63], v[232:233], v[80:81] op_sel_hi:[1,0,1]
	v_pk_fma_f32 v[92:93], v[60:61], v[162:163], v[74:75] op_sel_hi:[1,0,1]
	v_pk_fma_f32 v[96:97], v[62:63], v[162:163], v[64:65] op_sel_hi:[1,0,1]
	v_pk_fma_f32 v[60:61], v[100:101], v[230:231], v[122:123] op_sel_hi:[1,0,1]
	v_pk_fma_f32 v[62:63], v[102:103], v[230:231], v[114:115] op_sel_hi:[1,0,1]
	v_pk_fma_f32 v[64:65], v[100:101], v[230:231], v[106:107] op_sel:[0,1,0]
	v_pk_fma_f32 v[68:69], v[102:103], v[230:231], v[94:95] op_sel:[0,1,0]
	v_pk_fma_f32 v[72:73], v[100:101], v[232:233], v[88:89] op_sel_hi:[1,0,1]
	v_pk_fma_f32 v[74:75], v[102:103], v[232:233], v[84:85] op_sel_hi:[1,0,1]
	v_pk_fma_f32 v[70:71], v[100:101], v[162:163], v[70:71] op_sel_hi:[1,0,1]
	v_pk_fma_f32 v[66:67], v[102:103], v[162:163], v[66:67] op_sel_hi:[1,0,1]
	ds_read_b128 v[100:103], v225 offset:128
	s_waitcnt vmcnt(14)
	v_cvt_pk_f32_fp8_sdwa v[94:95], v56 src0_sel:WORD_1
	v_cvt_pk_f32_fp8_e32 v[88:89], v56
	s_waitcnt lgkmcnt(0)
; __device__ __forceinline__ void dsa_attend(const h16* PROJ, const unsigned short* IDX, const int* CNT, h16* MIXA, unsigned char* shm, unsigned* bar, unsigned xcc, unsigned xrank) {
;     ...
; #pragma unroll
;                 for (int e = 0; e < 16; ++e) { const int slot = s0 + 8 * e + r8;
;                     if ((e & 3) == 0) __builtin_amdgcn_sched_barrier(0);
;                     const f32x4 pp = *(const f32x4*)(Pl + ((size_t)wid * 256 + slot) * 4);
;                     const f32x2 p0 = (f32x2){pp.x, pp.x}, p1 = (f32x2){pp.y, pp.y}, p2 = (f32x2){pp.z, pp.z}, p3 = (f32x2){pp.w, pp.w};
;                     const unsigned wds[4] = {vv[e].x, vv[e].y, vv[e].z, vv[e].w};
; #pragma unroll
;                     for (int w = 0; w < 4; ++w) {
;                         const f32x2 lo = __builtin_amdgcn_cvt_pk_f32_fp8((int)wds[w], false), hi = __builtin_amdgcn_cvt_pk_f32_fp8((int)wds[w], true);
;                         oa2[0][2 * w] = __builtin_elementwise_fma(lo, p0, oa2[0][2 * w]); oa2[0][2 * w + 1] = __builtin_elementwise_fma(hi, p0, oa2[0][2 * w + 1]);
;                         oa2[1][2 * w] = __builtin_elementwise_fma(lo, p1, oa2[1][2 * w]); oa2[1][2 * w + 1] = __builtin_elementwise_fma(hi, p1, oa2[1][2 * w + 1]);
;                         oa2[2][2 * w] = __builtin_elementwise_fma(lo, p2, oa2[2][2 * w]); oa2[2][2 * w + 1] = __builtin_elementwise_fma(hi, p2, oa2[2][2 * w + 1]);
;                         oa2[3][2 * w] = __builtin_elementwise_fma(lo, p3, oa2[3][2 * w]); oa2[3][2 * w + 1] = __builtin_elementwise_fma(hi, p3, oa2[3][2 * w + 1]); }
;                 }
	v_pk_fma_f32 v[108:109], v[94:95], v[100:101], v[150:151] op_sel_hi:[1,0,1]
	v_cvt_pk_f32_fp8_e32 v[150:151], v57
	v_pk_fma_f32 v[114:115], v[88:89], v[100:101], v[152:153] op_sel:[0,1,0]
	v_cvt_pk_f32_fp8_sdwa v[56:57], v57 src0_sel:WORD_1
	v_mov_b32_e32 v84, v103
	v_pk_fma_f32 v[152:153], v[150:151], v[100:101], v[104:105] op_sel_hi:[1,0,1]
	v_cvt_pk_f32_fp8_e32 v[104:105], v58
	v_pk_fma_f32 v[120:121], v[94:95], v[100:101], v[154:155] op_sel:[0,1,0]
	v_pk_fma_f32 v[122:123], v[88:89], v[102:103], v[156:157] op_sel_hi:[1,0,1]
	v_pk_fma_f32 v[154:155], v[56:57], v[100:101], v[110:111] op_sel_hi:[1,0,1]
	v_pk_fma_f32 v[156:157], v[56:57], v[100:101], v[112:113] op_sel:[0,1,0]
	v_pk_fma_f32 v[118:119], v[56:57], v[102:103], v[118:119] op_sel_hi:[1,0,1]
	v_pk_fma_f32 v[56:57], v[56:57], v[84:85], v[126:127] op_sel_hi:[1,0,1]
	v_cvt_pk_f32_fp8_sdwa v[110:111], v58 src0_sel:WORD_1
	v_pk_fma_f32 v[126:127], v[104:105], v[100:101], v[86:87] op_sel:[0,1,0]
	v_cvt_pk_f32_fp8_e32 v[86:87], v59
	v_cvt_pk_f32_fp8_sdwa v[58:59], v59 src0_sel:WORD_1
	v_pk_fma_f32 v[106:107], v[88:89], v[100:101], v[148:149] op_sel_hi:[1,0,1]
	v_pk_fma_f32 v[148:149], v[94:95], v[102:103], v[158:159] op_sel_hi:[1,0,1]
	v_pk_fma_f32 v[94:95], v[94:95], v[84:85], v[186:187] op_sel_hi:[1,0,1]
	v_pk_fma_f32 v[186:187], v[86:87], v[100:101], v[60:61] op_sel_hi:[1,0,1]
	v_pk_fma_f32 v[226:227], v[58:59], v[100:101], v[62:63] op_sel_hi:[1,0,1]
	ds_read_b128 v[60:63], v225 offset:256
	v_pk_fma_f32 v[228:229], v[58:59], v[100:101], v[68:69] op_sel:[0,1,0]
	v_pk_fma_f32 v[232:233], v[58:59], v[102:103], v[74:75] op_sel_hi:[1,0,1]
	v_pk_fma_f32 v[66:67], v[58:59], v[84:85], v[66:67] op_sel_hi:[1,0,1]
	s_waitcnt vmcnt(13)
	v_cvt_pk_f32_fp8_e32 v[58:59], v52
	v_cvt_pk_f32_fp8_sdwa v[68:69], v52 src0_sel:WORD_1
	v_pk_fma_f32 v[88:89], v[88:89], v[84:85], v[184:185] op_sel_hi:[1,0,1]
	s_waitcnt lgkmcnt(0)
	v_mov_b32_e32 v162, v63
	v_pk_fma_f32 v[98:99], v[150:151], v[100:101], v[98:99] op_sel:[0,1,0]
	v_pk_fma_f32 v[116:117], v[150:151], v[102:103], v[116:117] op_sel_hi:[1,0,1]
	v_pk_fma_f32 v[124:125], v[150:151], v[84:85], v[124:125] op_sel_hi:[1,0,1]
	v_pk_fma_f32 v[76:77], v[104:105], v[100:101], v[76:77] op_sel_hi:[1,0,1]
	v_pk_fma_f32 v[78:79], v[110:111], v[100:101], v[78:79] op_sel_hi:[1,0,1]
	v_pk_fma_f32 v[150:151], v[110:111], v[100:101], v[90:91] op_sel:[0,1,0]
	v_pk_fma_f32 v[82:83], v[104:105], v[102:103], v[82:83] op_sel_hi:[1,0,1]
	v_pk_fma_f32 v[80:81], v[110:111], v[102:103], v[80:81] op_sel_hi:[1,0,1]
	v_pk_fma_f32 v[158:159], v[104:105], v[84:85], v[92:93] op_sel_hi:[1,0,1]
	v_pk_fma_f32 v[64:65], v[86:87], v[100:101], v[64:65] op_sel:[0,1,0]
	v_pk_fma_f32 v[230:231], v[86:87], v[102:103], v[72:73] op_sel_hi:[1,0,1]
	v_pk_fma_f32 v[100:101], v[58:59], v[60:61], v[106:107] op_sel_hi:[1,0,1]
	v_pk_fma_f32 v[102:103], v[68:69], v[60:61], v[108:109] op_sel_hi:[1,0,1]
	v_pk_fma_f32 v[104:105], v[58:59], v[60:61], v[114:115] op_sel:[0,1,0]
	v_pk_fma_f32 v[108:109], v[58:59], v[62:63], v[122:123] op_sel_hi:[1,0,1]
	v_pk_fma_f32 v[112:113], v[58:59], v[162:163], v[88:89] op_sel_hi:[1,0,1]
	v_cvt_pk_f32_fp8_e32 v[58:59], v53
	v_cvt_pk_f32_fp8_sdwa v[52:53], v53 src0_sel:WORD_1
	v_pk_fma_f32 v[234:235], v[86:87], v[84:85], v[70:71] op_sel_hi:[1,0,1]
	v_pk_fma_f32 v[114:115], v[68:69], v[162:163], v[94:95] op_sel_hi:[1,0,1]
	v_pk_fma_f32 v[88:89], v[58:59], v[60:61], v[98:99] op_sel:[0,1,0]
	v_pk_fma_f32 v[86:87], v[52:53], v[60:61], v[154:155] op_sel_hi:[1,0,1]
	v_pk_fma_f32 v[90:91], v[52:53], v[60:61], v[156:157] op_sel:[0,1,0]
	v_pk_fma_f32 v[92:93], v[58:59], v[62:63], v[116:117] op_sel_hi:[1,0,1]
	v_pk_fma_f32 v[94:95], v[52:53], v[62:63], v[118:119] op_sel_hi:[1,0,1]
	v_pk_fma_f32 v[98:99], v[52:53], v[162:163], v[56:57] op_sel_hi:[1,0,1]
	v_cvt_pk_f32_fp8_e32 v[52:53], v54
	v_cvt_pk_f32_fp8_sdwa v[56:57], v54 src0_sel:WORD_1
	v_cvt_pk_f32_fp8_e32 v[116:117], v55
	v_cvt_pk_f32_fp8_sdwa v[118:119], v55 src0_sel:WORD_1
	v_pk_fma_f32 v[184:185], v[110:111], v[84:85], v[96:97] op_sel_hi:[1,0,1]
	v_pk_fma_f32 v[106:107], v[68:69], v[60:61], v[120:121] op_sel:[0,1,0]
	v_pk_fma_f32 v[110:111], v[68:69], v[62:63], v[148:149] op_sel_hi:[1,0,1]
	v_pk_fma_f32 v[84:85], v[58:59], v[60:61], v[152:153] op_sel_hi:[1,0,1]
	v_pk_fma_f32 v[96:97], v[58:59], v[162:163], v[124:125] op_sel_hi:[1,0,1]
	v_pk_fma_f32 v[68:69], v[52:53], v[60:61], v[76:77] op_sel_hi:[1,0,1]
	v_pk_fma_f32 v[70:71], v[56:57], v[60:61], v[78:79] op_sel_hi:[1,0,1]
	v_pk_fma_f32 v[72:73], v[52:53], v[60:61], v[126:127] op_sel:[0,1,0]
	v_pk_fma_f32 v[74:75], v[56:57], v[60:61], v[150:151] op_sel:[0,1,0]
	v_pk_fma_f32 v[76:77], v[52:53], v[62:63], v[82:83] op_sel_hi:[1,0,1]
	v_pk_fma_f32 v[78:79], v[56:57], v[62:63], v[80:81] op_sel_hi:[1,0,1]
	v_pk_fma_f32 v[80:81], v[52:53], v[162:163], v[158:159] op_sel_hi:[1,0,1]
	v_pk_fma_f32 v[82:83], v[56:57], v[162:163], v[184:185] op_sel_hi:[1,0,1]
	v_pk_fma_f32 v[52:53], v[116:117], v[60:61], v[186:187] op_sel_hi:[1,0,1]
	v_pk_fma_f32 v[54:55], v[118:119], v[60:61], v[226:227] op_sel_hi:[1,0,1]
	v_pk_fma_f32 v[56:57], v[116:117], v[60:61], v[64:65] op_sel:[0,1,0]
	v_pk_fma_f32 v[58:59], v[118:119], v[60:61], v[228:229] op_sel:[0,1,0]
	v_pk_fma_f32 v[60:61], v[116:117], v[62:63], v[230:231] op_sel_hi:[1,0,1]
	v_pk_fma_f32 v[62:63], v[118:119], v[62:63], v[232:233] op_sel_hi:[1,0,1]
	v_pk_fma_f32 v[64:65], v[116:117], v[162:163], v[234:235] op_sel_hi:[1,0,1]
	v_pk_fma_f32 v[66:67], v[118:119], v[162:163], v[66:67] op_sel_hi:[1,0,1]
	ds_read_b128 v[116:119], v225 offset:384
	s_waitcnt vmcnt(12)
	v_cvt_pk_f32_fp8_e32 v[122:123], v48
	v_cvt_pk_f32_fp8_sdwa v[124:125], v48 src0_sel:WORD_1
	s_waitcnt lgkmcnt(0)
; __device__ __forceinline__ void dsa_attend(const h16* PROJ, const unsigned short* IDX, const int* CNT, h16* MIXA, unsigned char* shm, unsigned* bar, unsigned xcc, unsigned xrank) {
;     ...
; #pragma unroll
;                 for (int e = 0; e < 16; ++e) { const int slot = s0 + 8 * e + r8;
;                     if ((e & 3) == 0) __builtin_amdgcn_sched_barrier(0);
;                     const f32x4 pp = *(const f32x4*)(Pl + ((size_t)wid * 256 + slot) * 4);
;                     const f32x2 p0 = (f32x2){pp.x, pp.x}, p1 = (f32x2){pp.y, pp.y}, p2 = (f32x2){pp.z, pp.z}, p3 = (f32x2){pp.w, pp.w};
;                     const unsigned wds[4] = {vv[e].x, vv[e].y, vv[e].z, vv[e].w};
; #pragma unroll
;                     for (int w = 0; w < 4; ++w) {
;                         const f32x2 lo = __builtin_amdgcn_cvt_pk_f32_fp8((int)wds[w], false), hi = __builtin_amdgcn_cvt_pk_f32_fp8((int)wds[w], true);
;                         oa2[0][2 * w] = __builtin_elementwise_fma(lo, p0, oa2[0][2 * w]); oa2[0][2 * w + 1] = __builtin_elementwise_fma(hi, p0, oa2[0][2 * w + 1]);
;                         oa2[1][2 * w] = __builtin_elementwise_fma(lo, p1, oa2[1][2 * w]); oa2[1][2 * w + 1] = __builtin_elementwise_fma(hi, p1, oa2[1][2 * w + 1]);
;                         oa2[2][2 * w] = __builtin_elementwise_fma(lo, p2, oa2[2][2 * w]); oa2[2][2 * w + 1] = __builtin_elementwise_fma(hi, p2, oa2[2][2 * w + 1]);
;                         oa2[3][2 * w] = __builtin_elementwise_fma(lo, p3, oa2[3][2 * w]); oa2[3][2 * w + 1] = __builtin_elementwise_fma(hi, p3, oa2[3][2 * w + 1]); }
;                 }
	v_mov_b32_e32 v120, v119
	v_pk_fma_f32 v[100:101], v[122:123], v[116:117], v[100:101] op_sel_hi:[1,0,1]
	v_pk_fma_f32 v[104:105], v[122:123], v[116:117], v[104:105] op_sel:[0,1,0]
	v_pk_fma_f32 v[108:109], v[122:123], v[118:119], v[108:109] op_sel_hi:[1,0,1]
	v_pk_fma_f32 v[112:113], v[122:123], v[120:121], v[112:113] op_sel_hi:[1,0,1]
	v_cvt_pk_f32_fp8_e32 v[122:123], v49
	v_pk_fma_f32 v[102:103], v[124:125], v[116:117], v[102:103] op_sel_hi:[1,0,1]
	v_pk_fma_f32 v[106:107], v[124:125], v[116:117], v[106:107] op_sel:[0,1,0]
	v_pk_fma_f32 v[110:111], v[124:125], v[118:119], v[110:111] op_sel_hi:[1,0,1]
	v_pk_fma_f32 v[114:115], v[124:125], v[120:121], v[114:115] op_sel_hi:[1,0,1]
	v_cvt_pk_f32_fp8_sdwa v[48:49], v49 src0_sel:WORD_1
	v_pk_fma_f32 v[124:125], v[122:123], v[118:119], v[92:93] op_sel_hi:[1,0,1]
	v_cvt_pk_f32_fp8_e32 v[92:93], v50
	v_pk_fma_f32 v[84:85], v[122:123], v[116:117], v[84:85] op_sel_hi:[1,0,1]
	v_pk_fma_f32 v[126:127], v[48:49], v[118:119], v[94:95] op_sel_hi:[1,0,1]
	v_cvt_pk_f32_fp8_sdwa v[94:95], v50 src0_sel:WORD_1
	v_pk_fma_f32 v[148:149], v[92:93], v[118:119], v[76:77] op_sel_hi:[1,0,1]
	v_cvt_pk_f32_fp8_e32 v[76:77], v51
	v_cvt_pk_f32_fp8_sdwa v[50:51], v51 src0_sel:WORD_1
	v_pk_fma_f32 v[86:87], v[48:49], v[116:117], v[86:87] op_sel_hi:[1,0,1]
	v_pk_fma_f32 v[88:89], v[122:123], v[116:117], v[88:89] op_sel:[0,1,0]
	v_pk_fma_f32 v[90:91], v[48:49], v[116:117], v[90:91] op_sel:[0,1,0]
	v_pk_fma_f32 v[122:123], v[122:123], v[120:121], v[96:97] op_sel_hi:[1,0,1]
	v_pk_fma_f32 v[48:49], v[48:49], v[120:121], v[98:99] op_sel_hi:[1,0,1]
	v_pk_fma_f32 v[68:69], v[92:93], v[116:117], v[68:69] op_sel_hi:[1,0,1]
	v_pk_fma_f32 v[70:71], v[94:95], v[116:117], v[70:71] op_sel_hi:[1,0,1]
	v_pk_fma_f32 v[72:73], v[92:93], v[116:117], v[72:73] op_sel:[0,1,0]
	v_pk_fma_f32 v[74:75], v[94:95], v[116:117], v[74:75] op_sel:[0,1,0]
	v_pk_fma_f32 v[150:151], v[94:95], v[118:119], v[78:79] op_sel_hi:[1,0,1]
	v_pk_fma_f32 v[152:153], v[92:93], v[120:121], v[80:81] op_sel_hi:[1,0,1]
	v_pk_fma_f32 v[154:155], v[94:95], v[120:121], v[82:83] op_sel_hi:[1,0,1]
	v_pk_fma_f32 v[156:157], v[76:77], v[116:117], v[52:53] op_sel_hi:[1,0,1]
	v_pk_fma_f32 v[158:159], v[50:51], v[116:117], v[54:55] op_sel_hi:[1,0,1]
	v_pk_fma_f32 v[56:57], v[76:77], v[116:117], v[56:57] op_sel:[0,1,0]
	v_pk_fma_f32 v[58:59], v[50:51], v[116:117], v[58:59] op_sel:[0,1,0]
	v_pk_fma_f32 v[116:117], v[76:77], v[118:119], v[60:61] op_sel_hi:[1,0,1]
	v_pk_fma_f32 v[118:119], v[50:51], v[118:119], v[62:63] op_sel_hi:[1,0,1]
	v_pk_fma_f32 v[184:185], v[76:77], v[120:121], v[64:65] op_sel_hi:[1,0,1]
	v_pk_fma_f32 v[120:121], v[50:51], v[120:121], v[66:67] op_sel_hi:[1,0,1]
	ds_read_b128 v[52:55], v225 offset:512
	s_waitcnt vmcnt(11)
	v_cvt_pk_f32_fp8_e32 v[50:51], v44
	v_cvt_pk_f32_fp8_sdwa v[60:61], v44 src0_sel:WORD_1
	s_waitcnt lgkmcnt(0)
	v_mov_b32_e32 v162, v55
	v_pk_fma_f32 v[92:93], v[50:51], v[52:53], v[100:101] op_sel_hi:[1,0,1]
	v_pk_fma_f32 v[96:97], v[50:51], v[52:53], v[104:105] op_sel:[0,1,0]
	v_pk_fma_f32 v[100:101], v[50:51], v[54:55], v[108:109] op_sel_hi:[1,0,1]
	v_pk_fma_f32 v[104:105], v[50:51], v[162:163], v[112:113] op_sel_hi:[1,0,1]
	v_cvt_pk_f32_fp8_e32 v[50:51], v45
	v_cvt_pk_f32_fp8_sdwa v[44:45], v45 src0_sel:WORD_1
	v_pk_fma_f32 v[94:95], v[60:61], v[52:53], v[102:103] op_sel_hi:[1,0,1]
	v_pk_fma_f32 v[102:103], v[60:61], v[54:55], v[110:111] op_sel_hi:[1,0,1]
	v_cvt_pk_f32_fp8_e32 v[108:109], v47
	v_pk_fma_f32 v[78:79], v[44:45], v[52:53], v[86:87] op_sel_hi:[1,0,1]
	v_pk_fma_f32 v[82:83], v[44:45], v[52:53], v[90:91] op_sel:[0,1,0]
	v_pk_fma_f32 v[86:87], v[44:45], v[54:55], v[126:127] op_sel_hi:[1,0,1]
	v_pk_fma_f32 v[90:91], v[44:45], v[162:163], v[48:49] op_sel_hi:[1,0,1]
	v_cvt_pk_f32_fp8_e32 v[44:45], v46
	v_cvt_pk_f32_fp8_sdwa v[48:49], v46 src0_sel:WORD_1
	v_cvt_pk_f32_fp8_sdwa v[110:111], v47 src0_sel:WORD_1
	v_pk_fma_f32 v[98:99], v[60:61], v[52:53], v[106:107] op_sel:[0,1,0]
	v_pk_fma_f32 v[106:107], v[60:61], v[162:163], v[114:115] op_sel_hi:[1,0,1]
	v_pk_fma_f32 v[76:77], v[50:51], v[52:53], v[84:85] op_sel_hi:[1,0,1]
	v_pk_fma_f32 v[80:81], v[50:51], v[52:53], v[88:89] op_sel:[0,1,0]
	v_pk_fma_f32 v[84:85], v[50:51], v[54:55], v[124:125] op_sel_hi:[1,0,1]
	v_pk_fma_f32 v[88:89], v[50:51], v[162:163], v[122:123] op_sel_hi:[1,0,1]
	v_pk_fma_f32 v[60:61], v[44:45], v[52:53], v[68:69] op_sel_hi:[1,0,1]
	v_pk_fma_f32 v[62:63], v[48:49], v[52:53], v[70:71] op_sel_hi:[1,0,1]
	v_pk_fma_f32 v[64:65], v[44:45], v[52:53], v[72:73] op_sel:[0,1,0]
	v_pk_fma_f32 v[66:67], v[48:49], v[52:53], v[74:75] op_sel:[0,1,0]
	v_pk_fma_f32 v[68:69], v[44:45], v[54:55], v[148:149] op_sel_hi:[1,0,1]
	v_pk_fma_f32 v[70:71], v[48:49], v[54:55], v[150:151] op_sel_hi:[1,0,1]
	v_pk_fma_f32 v[72:73], v[44:45], v[162:163], v[152:153] op_sel_hi:[1,0,1]
	v_pk_fma_f32 v[74:75], v[48:49], v[162:163], v[154:155] op_sel_hi:[1,0,1]
	v_pk_fma_f32 v[44:45], v[108:109], v[52:53], v[156:157] op_sel_hi:[1,0,1]
	v_pk_fma_f32 v[46:47], v[110:111], v[52:53], v[158:159] op_sel_hi:[1,0,1]
	v_pk_fma_f32 v[48:49], v[108:109], v[52:53], v[56:57] op_sel:[0,1,0]
	v_pk_fma_f32 v[50:51], v[110:111], v[52:53], v[58:59] op_sel:[0,1,0]
	v_pk_fma_f32 v[52:53], v[108:109], v[54:55], v[116:117] op_sel_hi:[1,0,1]
	v_pk_fma_f32 v[54:55], v[110:111], v[54:55], v[118:119] op_sel_hi:[1,0,1]
	v_pk_fma_f32 v[56:57], v[108:109], v[162:163], v[184:185] op_sel_hi:[1,0,1]
	v_pk_fma_f32 v[58:59], v[110:111], v[162:163], v[120:121] op_sel_hi:[1,0,1]
	ds_read_b128 v[108:111], v225 offset:640
	s_waitcnt vmcnt(10)
	v_cvt_pk_f32_fp8_e32 v[114:115], v40
	v_cvt_pk_f32_fp8_sdwa v[116:117], v40 src0_sel:WORD_1
	s_waitcnt lgkmcnt(0)
; __device__ __forceinline__ void dsa_attend(const h16* PROJ, const unsigned short* IDX, const int* CNT, h16* MIXA, unsigned char* shm, unsigned* bar, unsigned xcc, unsigned xrank) {
;     ...
; #pragma unroll
;                 for (int e = 0; e < 16; ++e) { const int slot = s0 + 8 * e + r8;
;                     if ((e & 3) == 0) __builtin_amdgcn_sched_barrier(0);
;                     const f32x4 pp = *(const f32x4*)(Pl + ((size_t)wid * 256 + slot) * 4);
;                     const f32x2 p0 = (f32x2){pp.x, pp.x}, p1 = (f32x2){pp.y, pp.y}, p2 = (f32x2){pp.z, pp.z}, p3 = (f32x2){pp.w, pp.w};
;                     const unsigned wds[4] = {vv[e].x, vv[e].y, vv[e].z, vv[e].w};
; #pragma unroll
;                     for (int w = 0; w < 4; ++w) {
;                         const f32x2 lo = __builtin_amdgcn_cvt_pk_f32_fp8((int)wds[w], false), hi = __builtin_amdgcn_cvt_pk_f32_fp8((int)wds[w], true);
;                         oa2[0][2 * w] = __builtin_elementwise_fma(lo, p0, oa2[0][2 * w]); oa2[0][2 * w + 1] = __builtin_elementwise_fma(hi, p0, oa2[0][2 * w + 1]);
;                         oa2[1][2 * w] = __builtin_elementwise_fma(lo, p1, oa2[1][2 * w]); oa2[1][2 * w + 1] = __builtin_elementwise_fma(hi, p1, oa2[1][2 * w + 1]);
;                         oa2[2][2 * w] = __builtin_elementwise_fma(lo, p2, oa2[2][2 * w]); oa2[2][2 * w + 1] = __builtin_elementwise_fma(hi, p2, oa2[2][2 * w + 1]);
;                         oa2[3][2 * w] = __builtin_elementwise_fma(lo, p3, oa2[3][2 * w]); oa2[3][2 * w + 1] = __builtin_elementwise_fma(hi, p3, oa2[3][2 * w + 1]); }
;                 }
	v_mov_b32_e32 v112, v111
	v_pk_fma_f32 v[92:93], v[114:115], v[108:109], v[92:93] op_sel_hi:[1,0,1]
	v_pk_fma_f32 v[96:97], v[114:115], v[108:109], v[96:97] op_sel:[0,1,0]
	v_pk_fma_f32 v[100:101], v[114:115], v[110:111], v[100:101] op_sel_hi:[1,0,1]
	v_pk_fma_f32 v[104:105], v[114:115], v[112:113], v[104:105] op_sel_hi:[1,0,1]
	v_cvt_pk_f32_fp8_e32 v[114:115], v41
	v_pk_fma_f32 v[94:95], v[116:117], v[108:109], v[94:95] op_sel_hi:[1,0,1]
	v_pk_fma_f32 v[98:99], v[116:117], v[108:109], v[98:99] op_sel:[0,1,0]
	v_pk_fma_f32 v[102:103], v[116:117], v[110:111], v[102:103] op_sel_hi:[1,0,1]
	v_pk_fma_f32 v[106:107], v[116:117], v[112:113], v[106:107] op_sel_hi:[1,0,1]
	v_cvt_pk_f32_fp8_sdwa v[40:41], v41 src0_sel:WORD_1
	v_pk_fma_f32 v[116:117], v[114:115], v[110:111], v[84:85] op_sel_hi:[1,0,1]
	v_cvt_pk_f32_fp8_e32 v[84:85], v42
	v_pk_fma_f32 v[76:77], v[114:115], v[108:109], v[76:77] op_sel_hi:[1,0,1]
	v_pk_fma_f32 v[118:119], v[40:41], v[110:111], v[86:87] op_sel_hi:[1,0,1]
	v_cvt_pk_f32_fp8_sdwa v[86:87], v42 src0_sel:WORD_1
	v_pk_fma_f32 v[120:121], v[84:85], v[110:111], v[68:69] op_sel_hi:[1,0,1]
	v_cvt_pk_f32_fp8_e32 v[68:69], v43
	v_cvt_pk_f32_fp8_sdwa v[42:43], v43 src0_sel:WORD_1
	v_pk_fma_f32 v[78:79], v[40:41], v[108:109], v[78:79] op_sel_hi:[1,0,1]
	v_pk_fma_f32 v[80:81], v[114:115], v[108:109], v[80:81] op_sel:[0,1,0]
	v_pk_fma_f32 v[148:149], v[68:69], v[108:109], v[44:45] op_sel_hi:[1,0,1]
	v_pk_fma_f32 v[150:151], v[42:43], v[108:109], v[46:47] op_sel_hi:[1,0,1]
	ds_read_b128 v[44:47], v225 offset:768
	v_pk_fma_f32 v[82:83], v[40:41], v[108:109], v[82:83] op_sel:[0,1,0]
	v_pk_fma_f32 v[114:115], v[114:115], v[112:113], v[88:89] op_sel_hi:[1,0,1]
	v_pk_fma_f32 v[40:41], v[40:41], v[112:113], v[90:91] op_sel_hi:[1,0,1]
	v_pk_fma_f32 v[60:61], v[84:85], v[108:109], v[60:61] op_sel_hi:[1,0,1]
	v_pk_fma_f32 v[62:63], v[86:87], v[108:109], v[62:63] op_sel_hi:[1,0,1]
	v_pk_fma_f32 v[64:65], v[84:85], v[108:109], v[64:65] op_sel:[0,1,0]
	v_pk_fma_f32 v[66:67], v[86:87], v[108:109], v[66:67] op_sel:[0,1,0]
	v_pk_fma_f32 v[122:123], v[86:87], v[110:111], v[70:71] op_sel_hi:[1,0,1]
	v_pk_fma_f32 v[124:125], v[84:85], v[112:113], v[72:73] op_sel_hi:[1,0,1]
	v_pk_fma_f32 v[126:127], v[86:87], v[112:113], v[74:75] op_sel_hi:[1,0,1]
	v_pk_fma_f32 v[48:49], v[68:69], v[108:109], v[48:49] op_sel:[0,1,0]
	v_pk_fma_f32 v[50:51], v[42:43], v[108:109], v[50:51] op_sel:[0,1,0]
	v_pk_fma_f32 v[108:109], v[68:69], v[110:111], v[52:53] op_sel_hi:[1,0,1]
	v_pk_fma_f32 v[110:111], v[42:43], v[110:111], v[54:55] op_sel_hi:[1,0,1]
	v_pk_fma_f32 v[152:153], v[68:69], v[112:113], v[56:57] op_sel_hi:[1,0,1]
	v_pk_fma_f32 v[112:113], v[42:43], v[112:113], v[58:59] op_sel_hi:[1,0,1]
	s_waitcnt vmcnt(9)
	v_cvt_pk_f32_fp8_e32 v[42:43], v36
	s_waitcnt lgkmcnt(0)
	v_mov_b32_e32 v154, v47
	v_cvt_pk_f32_fp8_sdwa v[52:53], v36 src0_sel:WORD_1
	v_pk_fma_f32 v[84:85], v[42:43], v[44:45], v[92:93] op_sel_hi:[1,0,1]
	v_pk_fma_f32 v[88:89], v[42:43], v[44:45], v[96:97] op_sel:[0,1,0]
	v_pk_fma_f32 v[92:93], v[42:43], v[46:47], v[100:101] op_sel_hi:[1,0,1]
	v_pk_fma_f32 v[96:97], v[42:43], v[154:155], v[104:105] op_sel_hi:[1,0,1]
	v_cvt_pk_f32_fp8_e32 v[42:43], v37
	v_cvt_pk_f32_fp8_sdwa v[36:37], v37 src0_sel:WORD_1
	v_pk_fma_f32 v[86:87], v[52:53], v[44:45], v[94:95] op_sel_hi:[1,0,1]
	v_pk_fma_f32 v[94:95], v[52:53], v[46:47], v[102:103] op_sel_hi:[1,0,1]
	v_cvt_pk_f32_fp8_e32 v[100:101], v39
	v_pk_fma_f32 v[70:71], v[36:37], v[44:45], v[78:79] op_sel_hi:[1,0,1]
	v_pk_fma_f32 v[74:75], v[36:37], v[44:45], v[82:83] op_sel:[0,1,0]
	v_pk_fma_f32 v[78:79], v[36:37], v[46:47], v[118:119] op_sel_hi:[1,0,1]
	v_pk_fma_f32 v[82:83], v[36:37], v[154:155], v[40:41] op_sel_hi:[1,0,1]
	v_cvt_pk_f32_fp8_e32 v[36:37], v38
	v_cvt_pk_f32_fp8_sdwa v[40:41], v38 src0_sel:WORD_1
	v_cvt_pk_f32_fp8_sdwa v[102:103], v39 src0_sel:WORD_1
	v_pk_fma_f32 v[90:91], v[52:53], v[44:45], v[98:99] op_sel:[0,1,0]
	v_pk_fma_f32 v[98:99], v[52:53], v[154:155], v[106:107] op_sel_hi:[1,0,1]
	v_pk_fma_f32 v[68:69], v[42:43], v[44:45], v[76:77] op_sel_hi:[1,0,1]
	v_pk_fma_f32 v[72:73], v[42:43], v[44:45], v[80:81] op_sel:[0,1,0]
	v_pk_fma_f32 v[76:77], v[42:43], v[46:47], v[116:117] op_sel_hi:[1,0,1]
	v_pk_fma_f32 v[80:81], v[42:43], v[154:155], v[114:115] op_sel_hi:[1,0,1]
	v_pk_fma_f32 v[52:53], v[36:37], v[44:45], v[60:61] op_sel_hi:[1,0,1]
	v_pk_fma_f32 v[54:55], v[40:41], v[44:45], v[62:63] op_sel_hi:[1,0,1]
	v_pk_fma_f32 v[56:57], v[36:37], v[44:45], v[64:65] op_sel:[0,1,0]
	v_pk_fma_f32 v[58:59], v[40:41], v[44:45], v[66:67] op_sel:[0,1,0]
	v_pk_fma_f32 v[60:61], v[36:37], v[46:47], v[120:121] op_sel_hi:[1,0,1]
	v_pk_fma_f32 v[62:63], v[40:41], v[46:47], v[122:123] op_sel_hi:[1,0,1]
	v_pk_fma_f32 v[64:65], v[36:37], v[154:155], v[124:125] op_sel_hi:[1,0,1]
	v_pk_fma_f32 v[66:67], v[40:41], v[154:155], v[126:127] op_sel_hi:[1,0,1]
	v_pk_fma_f32 v[36:37], v[100:101], v[44:45], v[148:149] op_sel_hi:[1,0,1]
	v_pk_fma_f32 v[38:39], v[102:103], v[44:45], v[150:151] op_sel_hi:[1,0,1]
	v_pk_fma_f32 v[40:41], v[100:101], v[44:45], v[48:49] op_sel:[0,1,0]
	v_pk_fma_f32 v[42:43], v[102:103], v[44:45], v[50:51] op_sel:[0,1,0]
	v_pk_fma_f32 v[44:45], v[100:101], v[46:47], v[108:109] op_sel_hi:[1,0,1]
	v_pk_fma_f32 v[46:47], v[102:103], v[46:47], v[110:111] op_sel_hi:[1,0,1]
	v_pk_fma_f32 v[48:49], v[100:101], v[154:155], v[152:153] op_sel_hi:[1,0,1]
	v_pk_fma_f32 v[50:51], v[102:103], v[154:155], v[112:113] op_sel_hi:[1,0,1]
	ds_read_b128 v[100:103], v225 offset:896
	s_waitcnt vmcnt(8)
	v_cvt_pk_f32_fp8_e32 v[106:107], v28
	v_cvt_pk_f32_fp8_sdwa v[108:109], v28 src0_sel:WORD_1
	s_waitcnt lgkmcnt(0)
; __device__ __forceinline__ void dsa_attend(const h16* PROJ, const unsigned short* IDX, const int* CNT, h16* MIXA, unsigned char* shm, unsigned* bar, unsigned xcc, unsigned xrank) {
;     ...
; #pragma unroll
;                 for (int e = 0; e < 16; ++e) { const int slot = s0 + 8 * e + r8;
;                     if ((e & 3) == 0) __builtin_amdgcn_sched_barrier(0);
;                     const f32x4 pp = *(const f32x4*)(Pl + ((size_t)wid * 256 + slot) * 4);
;                     const f32x2 p0 = (f32x2){pp.x, pp.x}, p1 = (f32x2){pp.y, pp.y}, p2 = (f32x2){pp.z, pp.z}, p3 = (f32x2){pp.w, pp.w};
;                     const unsigned wds[4] = {vv[e].x, vv[e].y, vv[e].z, vv[e].w};
; #pragma unroll
;                     for (int w = 0; w < 4; ++w) {
;                         const f32x2 lo = __builtin_amdgcn_cvt_pk_f32_fp8((int)wds[w], false), hi = __builtin_amdgcn_cvt_pk_f32_fp8((int)wds[w], true);
;                         oa2[0][2 * w] = __builtin_elementwise_fma(lo, p0, oa2[0][2 * w]); oa2[0][2 * w + 1] = __builtin_elementwise_fma(hi, p0, oa2[0][2 * w + 1]);
;                         oa2[1][2 * w] = __builtin_elementwise_fma(lo, p1, oa2[1][2 * w]); oa2[1][2 * w + 1] = __builtin_elementwise_fma(hi, p1, oa2[1][2 * w + 1]);
;                         oa2[2][2 * w] = __builtin_elementwise_fma(lo, p2, oa2[2][2 * w]); oa2[2][2 * w + 1] = __builtin_elementwise_fma(hi, p2, oa2[2][2 * w + 1]);
;                         oa2[3][2 * w] = __builtin_elementwise_fma(lo, p3, oa2[3][2 * w]); oa2[3][2 * w + 1] = __builtin_elementwise_fma(hi, p3, oa2[3][2 * w + 1]); }
;                 }
	v_mov_b32_e32 v104, v103
	v_pk_fma_f32 v[84:85], v[106:107], v[100:101], v[84:85] op_sel_hi:[1,0,1]
	v_pk_fma_f32 v[88:89], v[106:107], v[100:101], v[88:89] op_sel:[0,1,0]
	v_pk_fma_f32 v[92:93], v[106:107], v[102:103], v[92:93] op_sel_hi:[1,0,1]
	v_pk_fma_f32 v[96:97], v[106:107], v[104:105], v[96:97] op_sel_hi:[1,0,1]
	v_cvt_pk_f32_fp8_e32 v[106:107], v29
	v_pk_fma_f32 v[86:87], v[108:109], v[100:101], v[86:87] op_sel_hi:[1,0,1]
	v_pk_fma_f32 v[90:91], v[108:109], v[100:101], v[90:91] op_sel:[0,1,0]
	v_pk_fma_f32 v[94:95], v[108:109], v[102:103], v[94:95] op_sel_hi:[1,0,1]
	v_pk_fma_f32 v[98:99], v[108:109], v[104:105], v[98:99] op_sel_hi:[1,0,1]
	v_cvt_pk_f32_fp8_sdwa v[28:29], v29 src0_sel:WORD_1
	v_pk_fma_f32 v[108:109], v[106:107], v[102:103], v[76:77] op_sel_hi:[1,0,1]
	v_cvt_pk_f32_fp8_e32 v[76:77], v30
	v_pk_fma_f32 v[68:69], v[106:107], v[100:101], v[68:69] op_sel_hi:[1,0,1]
	v_pk_fma_f32 v[110:111], v[28:29], v[102:103], v[78:79] op_sel_hi:[1,0,1]
	v_cvt_pk_f32_fp8_sdwa v[78:79], v30 src0_sel:WORD_1
	v_pk_fma_f32 v[112:113], v[76:77], v[102:103], v[60:61] op_sel_hi:[1,0,1]
	v_cvt_pk_f32_fp8_e32 v[60:61], v31
	v_cvt_pk_f32_fp8_sdwa v[30:31], v31 src0_sel:WORD_1
	v_pk_fma_f32 v[70:71], v[28:29], v[100:101], v[70:71] op_sel_hi:[1,0,1]
	v_pk_fma_f32 v[72:73], v[106:107], v[100:101], v[72:73] op_sel:[0,1,0]
	v_pk_fma_f32 v[74:75], v[28:29], v[100:101], v[74:75] op_sel:[0,1,0]
	v_pk_fma_f32 v[106:107], v[106:107], v[104:105], v[80:81] op_sel_hi:[1,0,1]
	v_pk_fma_f32 v[28:29], v[28:29], v[104:105], v[82:83] op_sel_hi:[1,0,1]
	v_pk_fma_f32 v[52:53], v[76:77], v[100:101], v[52:53] op_sel_hi:[1,0,1]
	v_pk_fma_f32 v[54:55], v[78:79], v[100:101], v[54:55] op_sel_hi:[1,0,1]
	v_pk_fma_f32 v[56:57], v[76:77], v[100:101], v[56:57] op_sel:[0,1,0]
	v_pk_fma_f32 v[58:59], v[78:79], v[100:101], v[58:59] op_sel:[0,1,0]
	v_pk_fma_f32 v[114:115], v[78:79], v[102:103], v[62:63] op_sel_hi:[1,0,1]
	v_pk_fma_f32 v[116:117], v[76:77], v[104:105], v[64:65] op_sel_hi:[1,0,1]
	v_pk_fma_f32 v[118:119], v[78:79], v[104:105], v[66:67] op_sel_hi:[1,0,1]
	v_pk_fma_f32 v[120:121], v[60:61], v[100:101], v[36:37] op_sel_hi:[1,0,1]
	v_pk_fma_f32 v[122:123], v[30:31], v[100:101], v[38:39] op_sel_hi:[1,0,1]
	v_pk_fma_f32 v[40:41], v[60:61], v[100:101], v[40:41] op_sel:[0,1,0]
	v_pk_fma_f32 v[42:43], v[30:31], v[100:101], v[42:43] op_sel:[0,1,0]
	v_pk_fma_f32 v[100:101], v[60:61], v[102:103], v[44:45] op_sel_hi:[1,0,1]
	v_pk_fma_f32 v[102:103], v[30:31], v[102:103], v[46:47] op_sel_hi:[1,0,1]
	v_pk_fma_f32 v[124:125], v[60:61], v[104:105], v[48:49] op_sel_hi:[1,0,1]
	v_pk_fma_f32 v[104:105], v[30:31], v[104:105], v[50:51] op_sel_hi:[1,0,1]
	ds_read_b128 v[36:39], v225 offset:1024
	s_waitcnt vmcnt(7)
	v_cvt_pk_f32_fp8_e32 v[30:31], v32
	v_cvt_pk_f32_fp8_sdwa v[44:45], v32 src0_sel:WORD_1
	s_waitcnt lgkmcnt(0)
	v_mov_b32_e32 v126, v39
	v_pk_fma_f32 v[76:77], v[30:31], v[36:37], v[84:85] op_sel_hi:[1,0,1]
	v_pk_fma_f32 v[80:81], v[30:31], v[36:37], v[88:89] op_sel:[0,1,0]
	v_pk_fma_f32 v[84:85], v[30:31], v[38:39], v[92:93] op_sel_hi:[1,0,1]
	v_pk_fma_f32 v[88:89], v[30:31], v[126:127], v[96:97] op_sel_hi:[1,0,1]
	v_cvt_pk_f32_fp8_e32 v[30:31], v33
	v_cvt_pk_f32_fp8_sdwa v[32:33], v33 src0_sel:WORD_1
	v_pk_fma_f32 v[78:79], v[44:45], v[36:37], v[86:87] op_sel_hi:[1,0,1]
	v_pk_fma_f32 v[86:87], v[44:45], v[38:39], v[94:95] op_sel_hi:[1,0,1]
	v_pk_fma_f32 v[60:61], v[30:31], v[36:37], v[68:69] op_sel_hi:[1,0,1]
	v_pk_fma_f32 v[64:65], v[30:31], v[36:37], v[72:73] op_sel:[0,1,0]
	v_pk_fma_f32 v[66:67], v[32:33], v[36:37], v[74:75] op_sel:[0,1,0]
	v_pk_fma_f32 v[68:69], v[30:31], v[38:39], v[108:109] op_sel_hi:[1,0,1]
	v_pk_fma_f32 v[72:73], v[30:31], v[126:127], v[106:107] op_sel_hi:[1,0,1]
	v_pk_fma_f32 v[74:75], v[32:33], v[126:127], v[28:29] op_sel_hi:[1,0,1]
	v_cvt_pk_f32_fp8_e32 v[28:29], v34
	v_cvt_pk_f32_fp8_sdwa v[30:31], v34 src0_sel:WORD_1
	v_cvt_pk_f32_fp8_e32 v[92:93], v35
	v_cvt_pk_f32_fp8_sdwa v[94:95], v35 src0_sel:WORD_1
	v_pk_fma_f32 v[82:83], v[44:45], v[36:37], v[90:91] op_sel:[0,1,0]
	v_pk_fma_f32 v[90:91], v[44:45], v[126:127], v[98:99] op_sel_hi:[1,0,1]
	v_pk_fma_f32 v[62:63], v[32:33], v[36:37], v[70:71] op_sel_hi:[1,0,1]
	v_pk_fma_f32 v[70:71], v[32:33], v[38:39], v[110:111] op_sel_hi:[1,0,1]
	v_pk_fma_f32 v[44:45], v[28:29], v[36:37], v[52:53] op_sel_hi:[1,0,1]
	v_pk_fma_f32 v[46:47], v[30:31], v[36:37], v[54:55] op_sel_hi:[1,0,1]
	v_pk_fma_f32 v[48:49], v[28:29], v[36:37], v[56:57] op_sel:[0,1,0]
	v_pk_fma_f32 v[50:51], v[30:31], v[36:37], v[58:59] op_sel:[0,1,0]
	v_pk_fma_f32 v[52:53], v[28:29], v[38:39], v[112:113] op_sel_hi:[1,0,1]
	v_pk_fma_f32 v[54:55], v[30:31], v[38:39], v[114:115] op_sel_hi:[1,0,1]
	v_pk_fma_f32 v[56:57], v[28:29], v[126:127], v[116:117] op_sel_hi:[1,0,1]
	v_pk_fma_f32 v[58:59], v[30:31], v[126:127], v[118:119] op_sel_hi:[1,0,1]
	v_pk_fma_f32 v[28:29], v[92:93], v[36:37], v[120:121] op_sel_hi:[1,0,1]
	v_pk_fma_f32 v[30:31], v[94:95], v[36:37], v[122:123] op_sel_hi:[1,0,1]
	v_pk_fma_f32 v[32:33], v[92:93], v[36:37], v[40:41] op_sel:[0,1,0]
	v_pk_fma_f32 v[34:35], v[94:95], v[36:37], v[42:43] op_sel:[0,1,0]
	v_pk_fma_f32 v[36:37], v[92:93], v[38:39], v[100:101] op_sel_hi:[1,0,1]
	v_pk_fma_f32 v[38:39], v[94:95], v[38:39], v[102:103] op_sel_hi:[1,0,1]
	v_pk_fma_f32 v[40:41], v[92:93], v[126:127], v[124:125] op_sel_hi:[1,0,1]
	v_pk_fma_f32 v[42:43], v[94:95], v[126:127], v[104:105] op_sel_hi:[1,0,1]
	ds_read_b128 v[92:95], v225 offset:1152
	s_waitcnt vmcnt(6)
	v_cvt_pk_f32_fp8_e32 v[98:99], v24
	v_cvt_pk_f32_fp8_sdwa v[100:101], v24 src0_sel:WORD_1
	s_waitcnt lgkmcnt(0)
; __device__ __forceinline__ void dsa_attend(const h16* PROJ, const unsigned short* IDX, const int* CNT, h16* MIXA, unsigned char* shm, unsigned* bar, unsigned xcc, unsigned xrank) {
;     ...
; #pragma unroll
;                 for (int e = 0; e < 16; ++e) { const int slot = s0 + 8 * e + r8;
;                     if ((e & 3) == 0) __builtin_amdgcn_sched_barrier(0);
;                     const f32x4 pp = *(const f32x4*)(Pl + ((size_t)wid * 256 + slot) * 4);
;                     const f32x2 p0 = (f32x2){pp.x, pp.x}, p1 = (f32x2){pp.y, pp.y}, p2 = (f32x2){pp.z, pp.z}, p3 = (f32x2){pp.w, pp.w};
;                     const unsigned wds[4] = {vv[e].x, vv[e].y, vv[e].z, vv[e].w};
; #pragma unroll
;                     for (int w = 0; w < 4; ++w) {
;                         const f32x2 lo = __builtin_amdgcn_cvt_pk_f32_fp8((int)wds[w], false), hi = __builtin_amdgcn_cvt_pk_f32_fp8((int)wds[w], true);
;                         oa2[0][2 * w] = __builtin_elementwise_fma(lo, p0, oa2[0][2 * w]); oa2[0][2 * w + 1] = __builtin_elementwise_fma(hi, p0, oa2[0][2 * w + 1]);
;                         oa2[1][2 * w] = __builtin_elementwise_fma(lo, p1, oa2[1][2 * w]); oa2[1][2 * w + 1] = __builtin_elementwise_fma(hi, p1, oa2[1][2 * w + 1]);
;                         oa2[2][2 * w] = __builtin_elementwise_fma(lo, p2, oa2[2][2 * w]); oa2[2][2 * w + 1] = __builtin_elementwise_fma(hi, p2, oa2[2][2 * w + 1]);
;                         oa2[3][2 * w] = __builtin_elementwise_fma(lo, p3, oa2[3][2 * w]); oa2[3][2 * w + 1] = __builtin_elementwise_fma(hi, p3, oa2[3][2 * w + 1]); }
;                 }
	v_mov_b32_e32 v96, v95
	v_pk_fma_f32 v[76:77], v[98:99], v[92:93], v[76:77] op_sel_hi:[1,0,1]
	v_pk_fma_f32 v[80:81], v[98:99], v[92:93], v[80:81] op_sel:[0,1,0]
	v_pk_fma_f32 v[84:85], v[98:99], v[94:95], v[84:85] op_sel_hi:[1,0,1]
	v_pk_fma_f32 v[88:89], v[98:99], v[96:97], v[88:89] op_sel_hi:[1,0,1]
	v_cvt_pk_f32_fp8_e32 v[98:99], v25
	v_pk_fma_f32 v[78:79], v[100:101], v[92:93], v[78:79] op_sel_hi:[1,0,1]
	v_pk_fma_f32 v[82:83], v[100:101], v[92:93], v[82:83] op_sel:[0,1,0]
	v_pk_fma_f32 v[86:87], v[100:101], v[94:95], v[86:87] op_sel_hi:[1,0,1]
	v_pk_fma_f32 v[90:91], v[100:101], v[96:97], v[90:91] op_sel_hi:[1,0,1]
	v_cvt_pk_f32_fp8_sdwa v[24:25], v25 src0_sel:WORD_1
	v_pk_fma_f32 v[100:101], v[98:99], v[94:95], v[68:69] op_sel_hi:[1,0,1]
	v_cvt_pk_f32_fp8_e32 v[68:69], v26
	v_pk_fma_f32 v[60:61], v[98:99], v[92:93], v[60:61] op_sel_hi:[1,0,1]
	v_pk_fma_f32 v[102:103], v[24:25], v[94:95], v[70:71] op_sel_hi:[1,0,1]
	v_cvt_pk_f32_fp8_sdwa v[70:71], v26 src0_sel:WORD_1
	v_pk_fma_f32 v[104:105], v[68:69], v[94:95], v[52:53] op_sel_hi:[1,0,1]
	v_cvt_pk_f32_fp8_e32 v[52:53], v27
	v_cvt_pk_f32_fp8_sdwa v[26:27], v27 src0_sel:WORD_1
	v_pk_fma_f32 v[62:63], v[24:25], v[92:93], v[62:63] op_sel_hi:[1,0,1]
	v_pk_fma_f32 v[64:65], v[98:99], v[92:93], v[64:65] op_sel:[0,1,0]
	v_pk_fma_f32 v[112:113], v[52:53], v[92:93], v[28:29] op_sel_hi:[1,0,1]
	v_pk_fma_f32 v[114:115], v[26:27], v[92:93], v[30:31] op_sel_hi:[1,0,1]
	ds_read_b128 v[28:31], v225 offset:1280
	v_pk_fma_f32 v[66:67], v[24:25], v[92:93], v[66:67] op_sel:[0,1,0]
	v_pk_fma_f32 v[98:99], v[98:99], v[96:97], v[72:73] op_sel_hi:[1,0,1]
	v_pk_fma_f32 v[24:25], v[24:25], v[96:97], v[74:75] op_sel_hi:[1,0,1]
	v_pk_fma_f32 v[44:45], v[68:69], v[92:93], v[44:45] op_sel_hi:[1,0,1]
	v_pk_fma_f32 v[46:47], v[70:71], v[92:93], v[46:47] op_sel_hi:[1,0,1]
	v_pk_fma_f32 v[48:49], v[68:69], v[92:93], v[48:49] op_sel:[0,1,0]
	v_pk_fma_f32 v[50:51], v[70:71], v[92:93], v[50:51] op_sel:[0,1,0]
	v_pk_fma_f32 v[106:107], v[70:71], v[94:95], v[54:55] op_sel_hi:[1,0,1]
	v_pk_fma_f32 v[108:109], v[68:69], v[96:97], v[56:57] op_sel_hi:[1,0,1]
	v_pk_fma_f32 v[110:111], v[70:71], v[96:97], v[58:59] op_sel_hi:[1,0,1]
	v_pk_fma_f32 v[32:33], v[52:53], v[92:93], v[32:33] op_sel:[0,1,0]
	v_pk_fma_f32 v[34:35], v[26:27], v[92:93], v[34:35] op_sel:[0,1,0]
	v_pk_fma_f32 v[92:93], v[52:53], v[94:95], v[36:37] op_sel_hi:[1,0,1]
	v_pk_fma_f32 v[94:95], v[26:27], v[94:95], v[38:39] op_sel_hi:[1,0,1]
	v_pk_fma_f32 v[116:117], v[52:53], v[96:97], v[40:41] op_sel_hi:[1,0,1]
	v_pk_fma_f32 v[96:97], v[26:27], v[96:97], v[42:43] op_sel_hi:[1,0,1]
	s_waitcnt vmcnt(5)
	v_cvt_pk_f32_fp8_e32 v[26:27], v20
	s_waitcnt lgkmcnt(0)
	v_mov_b32_e32 v118, v31
	v_cvt_pk_f32_fp8_sdwa v[36:37], v20 src0_sel:WORD_1
	v_pk_fma_f32 v[68:69], v[26:27], v[28:29], v[76:77] op_sel_hi:[1,0,1]
	v_pk_fma_f32 v[72:73], v[26:27], v[28:29], v[80:81] op_sel:[0,1,0]
	v_pk_fma_f32 v[76:77], v[26:27], v[30:31], v[84:85] op_sel_hi:[1,0,1]
	v_pk_fma_f32 v[80:81], v[26:27], v[118:119], v[88:89] op_sel_hi:[1,0,1]
	v_cvt_pk_f32_fp8_e32 v[26:27], v21
	v_cvt_pk_f32_fp8_sdwa v[20:21], v21 src0_sel:WORD_1
	v_pk_fma_f32 v[70:71], v[36:37], v[28:29], v[78:79] op_sel_hi:[1,0,1]
	v_pk_fma_f32 v[78:79], v[36:37], v[30:31], v[86:87] op_sel_hi:[1,0,1]
	v_cvt_pk_f32_fp8_e32 v[84:85], v23
	v_pk_fma_f32 v[54:55], v[20:21], v[28:29], v[62:63] op_sel_hi:[1,0,1]
	v_pk_fma_f32 v[58:59], v[20:21], v[28:29], v[66:67] op_sel:[0,1,0]
	v_pk_fma_f32 v[62:63], v[20:21], v[30:31], v[102:103] op_sel_hi:[1,0,1]
	v_pk_fma_f32 v[66:67], v[20:21], v[118:119], v[24:25] op_sel_hi:[1,0,1]
	v_cvt_pk_f32_fp8_e32 v[20:21], v22
	v_cvt_pk_f32_fp8_sdwa v[24:25], v22 src0_sel:WORD_1
	v_cvt_pk_f32_fp8_sdwa v[86:87], v23 src0_sel:WORD_1
	v_pk_fma_f32 v[74:75], v[36:37], v[28:29], v[82:83] op_sel:[0,1,0]
	v_pk_fma_f32 v[82:83], v[36:37], v[118:119], v[90:91] op_sel_hi:[1,0,1]
	v_pk_fma_f32 v[52:53], v[26:27], v[28:29], v[60:61] op_sel_hi:[1,0,1]
	v_pk_fma_f32 v[56:57], v[26:27], v[28:29], v[64:65] op_sel:[0,1,0]
	v_pk_fma_f32 v[60:61], v[26:27], v[30:31], v[100:101] op_sel_hi:[1,0,1]
	v_pk_fma_f32 v[64:65], v[26:27], v[118:119], v[98:99] op_sel_hi:[1,0,1]
	v_pk_fma_f32 v[36:37], v[20:21], v[28:29], v[44:45] op_sel_hi:[1,0,1]
	v_pk_fma_f32 v[38:39], v[24:25], v[28:29], v[46:47] op_sel_hi:[1,0,1]
	v_pk_fma_f32 v[40:41], v[20:21], v[28:29], v[48:49] op_sel:[0,1,0]
	v_pk_fma_f32 v[42:43], v[24:25], v[28:29], v[50:51] op_sel:[0,1,0]
	v_pk_fma_f32 v[44:45], v[20:21], v[30:31], v[104:105] op_sel_hi:[1,0,1]
	v_pk_fma_f32 v[46:47], v[24:25], v[30:31], v[106:107] op_sel_hi:[1,0,1]
	v_pk_fma_f32 v[48:49], v[20:21], v[118:119], v[108:109] op_sel_hi:[1,0,1]
	v_pk_fma_f32 v[50:51], v[24:25], v[118:119], v[110:111] op_sel_hi:[1,0,1]
	v_pk_fma_f32 v[20:21], v[84:85], v[28:29], v[112:113] op_sel_hi:[1,0,1]
	v_pk_fma_f32 v[22:23], v[86:87], v[28:29], v[114:115] op_sel_hi:[1,0,1]
	v_pk_fma_f32 v[24:25], v[84:85], v[28:29], v[32:33] op_sel:[0,1,0]
	v_pk_fma_f32 v[26:27], v[86:87], v[28:29], v[34:35] op_sel:[0,1,0]
	v_pk_fma_f32 v[28:29], v[84:85], v[30:31], v[92:93] op_sel_hi:[1,0,1]
	v_pk_fma_f32 v[30:31], v[86:87], v[30:31], v[94:95] op_sel_hi:[1,0,1]
	v_pk_fma_f32 v[32:33], v[84:85], v[118:119], v[116:117] op_sel_hi:[1,0,1]
	v_pk_fma_f32 v[34:35], v[86:87], v[118:119], v[96:97] op_sel_hi:[1,0,1]
	ds_read_b128 v[84:87], v225 offset:1408
	s_waitcnt vmcnt(4)
	v_cvt_pk_f32_fp8_e32 v[90:91], v16
	v_cvt_pk_f32_fp8_sdwa v[92:93], v16 src0_sel:WORD_1
	s_waitcnt lgkmcnt(0)
; __device__ __forceinline__ void dsa_attend(const h16* PROJ, const unsigned short* IDX, const int* CNT, h16* MIXA, unsigned char* shm, unsigned* bar, unsigned xcc, unsigned xrank) {
;     ...
; #pragma unroll
;                 for (int e = 0; e < 16; ++e) { const int slot = s0 + 8 * e + r8;
;                     if ((e & 3) == 0) __builtin_amdgcn_sched_barrier(0);
;                     const f32x4 pp = *(const f32x4*)(Pl + ((size_t)wid * 256 + slot) * 4);
;                     const f32x2 p0 = (f32x2){pp.x, pp.x}, p1 = (f32x2){pp.y, pp.y}, p2 = (f32x2){pp.z, pp.z}, p3 = (f32x2){pp.w, pp.w};
;                     const unsigned wds[4] = {vv[e].x, vv[e].y, vv[e].z, vv[e].w};
; #pragma unroll
;                     for (int w = 0; w < 4; ++w) {
;                         const f32x2 lo = __builtin_amdgcn_cvt_pk_f32_fp8((int)wds[w], false), hi = __builtin_amdgcn_cvt_pk_f32_fp8((int)wds[w], true);
;                         oa2[0][2 * w] = __builtin_elementwise_fma(lo, p0, oa2[0][2 * w]); oa2[0][2 * w + 1] = __builtin_elementwise_fma(hi, p0, oa2[0][2 * w + 1]);
;                         oa2[1][2 * w] = __builtin_elementwise_fma(lo, p1, oa2[1][2 * w]); oa2[1][2 * w + 1] = __builtin_elementwise_fma(hi, p1, oa2[1][2 * w + 1]);
;                         oa2[2][2 * w] = __builtin_elementwise_fma(lo, p2, oa2[2][2 * w]); oa2[2][2 * w + 1] = __builtin_elementwise_fma(hi, p2, oa2[2][2 * w + 1]);
;                         oa2[3][2 * w] = __builtin_elementwise_fma(lo, p3, oa2[3][2 * w]); oa2[3][2 * w + 1] = __builtin_elementwise_fma(hi, p3, oa2[3][2 * w + 1]); }
;                 }
	v_mov_b32_e32 v88, v87
	v_pk_fma_f32 v[68:69], v[90:91], v[84:85], v[68:69] op_sel_hi:[1,0,1]
	v_pk_fma_f32 v[72:73], v[90:91], v[84:85], v[72:73] op_sel:[0,1,0]
	v_pk_fma_f32 v[76:77], v[90:91], v[86:87], v[76:77] op_sel_hi:[1,0,1]
	v_pk_fma_f32 v[80:81], v[90:91], v[88:89], v[80:81] op_sel_hi:[1,0,1]
	v_cvt_pk_f32_fp8_e32 v[90:91], v17
	v_cvt_pk_f32_fp8_sdwa v[16:17], v17 src0_sel:WORD_1
	v_pk_fma_f32 v[70:71], v[92:93], v[84:85], v[70:71] op_sel_hi:[1,0,1]
	v_pk_fma_f32 v[74:75], v[92:93], v[84:85], v[74:75] op_sel:[0,1,0]
	v_pk_fma_f32 v[52:53], v[90:91], v[84:85], v[52:53] op_sel_hi:[1,0,1]
	v_pk_fma_f32 v[54:55], v[16:17], v[84:85], v[54:55] op_sel_hi:[1,0,1]
	v_pk_fma_f32 v[58:59], v[16:17], v[84:85], v[58:59] op_sel:[0,1,0]
	v_pk_fma_f32 v[62:63], v[16:17], v[86:87], v[62:63] op_sel_hi:[1,0,1]
	v_pk_fma_f32 v[66:67], v[16:17], v[88:89], v[66:67] op_sel_hi:[1,0,1]
	v_cvt_pk_f32_fp8_e32 v[16:17], v18
	v_pk_fma_f32 v[56:57], v[90:91], v[84:85], v[56:57] op_sel:[0,1,0]
	v_pk_fma_f32 v[60:61], v[90:91], v[86:87], v[60:61] op_sel_hi:[1,0,1]
	v_pk_fma_f32 v[64:65], v[90:91], v[88:89], v[64:65] op_sel_hi:[1,0,1]
	v_cvt_pk_f32_fp8_sdwa v[90:91], v18 src0_sel:WORD_1
	v_pk_fma_f32 v[36:37], v[16:17], v[84:85], v[36:37] op_sel_hi:[1,0,1]
	v_pk_fma_f32 v[40:41], v[16:17], v[84:85], v[40:41] op_sel:[0,1,0]
	v_pk_fma_f32 v[44:45], v[16:17], v[86:87], v[44:45] op_sel_hi:[1,0,1]
	v_pk_fma_f32 v[48:49], v[16:17], v[88:89], v[48:49] op_sel_hi:[1,0,1]
	v_cvt_pk_f32_fp8_e32 v[16:17], v19
	v_cvt_pk_f32_fp8_sdwa v[18:19], v19 src0_sel:WORD_1
	v_pk_fma_f32 v[78:79], v[92:93], v[86:87], v[78:79] op_sel_hi:[1,0,1]
	v_pk_fma_f32 v[82:83], v[92:93], v[88:89], v[82:83] op_sel_hi:[1,0,1]
	v_pk_fma_f32 v[38:39], v[90:91], v[84:85], v[38:39] op_sel_hi:[1,0,1]
	v_pk_fma_f32 v[42:43], v[90:91], v[84:85], v[42:43] op_sel:[0,1,0]
	v_pk_fma_f32 v[46:47], v[90:91], v[86:87], v[46:47] op_sel_hi:[1,0,1]
	v_pk_fma_f32 v[50:51], v[90:91], v[88:89], v[50:51] op_sel_hi:[1,0,1]
	v_pk_fma_f32 v[20:21], v[16:17], v[84:85], v[20:21] op_sel_hi:[1,0,1]
	v_pk_fma_f32 v[22:23], v[18:19], v[84:85], v[22:23] op_sel_hi:[1,0,1]
	v_pk_fma_f32 v[24:25], v[16:17], v[84:85], v[24:25] op_sel:[0,1,0]
	v_pk_fma_f32 v[26:27], v[18:19], v[84:85], v[26:27] op_sel:[0,1,0]
	v_pk_fma_f32 v[28:29], v[16:17], v[86:87], v[28:29] op_sel_hi:[1,0,1]
	v_pk_fma_f32 v[30:31], v[18:19], v[86:87], v[30:31] op_sel_hi:[1,0,1]
	v_pk_fma_f32 v[32:33], v[16:17], v[88:89], v[32:33] op_sel_hi:[1,0,1]
	v_pk_fma_f32 v[34:35], v[18:19], v[88:89], v[34:35] op_sel_hi:[1,0,1]
	ds_read_b128 v[16:19], v225 offset:1536
	s_waitcnt vmcnt(3)
	v_cvt_pk_f32_fp8_e32 v[86:87], v12
	v_cvt_pk_f32_fp8_sdwa v[88:89], v12 src0_sel:WORD_1
	s_addk_i32 s50, 0x80
	s_cmp_ge_u32 s50, s67
	s_waitcnt lgkmcnt(0)
	v_mov_b32_e32 v84, v19
	v_pk_fma_f32 v[68:69], v[86:87], v[16:17], v[68:69] op_sel_hi:[1,0,1]
	v_pk_fma_f32 v[72:73], v[86:87], v[16:17], v[72:73] op_sel:[0,1,0]
	v_pk_fma_f32 v[76:77], v[86:87], v[18:19], v[76:77] op_sel_hi:[1,0,1]
	v_pk_fma_f32 v[80:81], v[86:87], v[84:85], v[80:81] op_sel_hi:[1,0,1]
	v_cvt_pk_f32_fp8_e32 v[86:87], v13
	v_cvt_pk_f32_fp8_sdwa v[12:13], v13 src0_sel:WORD_1
	v_pk_fma_f32 v[70:71], v[88:89], v[16:17], v[70:71] op_sel_hi:[1,0,1]
	v_pk_fma_f32 v[74:75], v[88:89], v[16:17], v[74:75] op_sel:[0,1,0]
	v_pk_fma_f32 v[52:53], v[86:87], v[16:17], v[52:53] op_sel_hi:[1,0,1]
	v_pk_fma_f32 v[54:55], v[12:13], v[16:17], v[54:55] op_sel_hi:[1,0,1]
	v_pk_fma_f32 v[58:59], v[12:13], v[16:17], v[58:59] op_sel:[0,1,0]
	v_pk_fma_f32 v[62:63], v[12:13], v[18:19], v[62:63] op_sel_hi:[1,0,1]
	v_pk_fma_f32 v[66:67], v[12:13], v[84:85], v[66:67] op_sel_hi:[1,0,1]
	v_cvt_pk_f32_fp8_e32 v[12:13], v14
	v_pk_fma_f32 v[56:57], v[86:87], v[16:17], v[56:57] op_sel:[0,1,0]
	v_pk_fma_f32 v[60:61], v[86:87], v[18:19], v[60:61] op_sel_hi:[1,0,1]
	v_pk_fma_f32 v[64:65], v[86:87], v[84:85], v[64:65] op_sel_hi:[1,0,1]
	v_cvt_pk_f32_fp8_sdwa v[86:87], v14 src0_sel:WORD_1
	v_pk_fma_f32 v[36:37], v[12:13], v[16:17], v[36:37] op_sel_hi:[1,0,1]
	v_pk_fma_f32 v[40:41], v[12:13], v[16:17], v[40:41] op_sel:[0,1,0]
	v_pk_fma_f32 v[44:45], v[12:13], v[18:19], v[44:45] op_sel_hi:[1,0,1]
	v_pk_fma_f32 v[48:49], v[12:13], v[84:85], v[48:49] op_sel_hi:[1,0,1]
	v_cvt_pk_f32_fp8_e32 v[12:13], v15
	v_cvt_pk_f32_fp8_sdwa v[14:15], v15 src0_sel:WORD_1
	v_pk_fma_f32 v[78:79], v[88:89], v[18:19], v[78:79] op_sel_hi:[1,0,1]
	v_pk_fma_f32 v[38:39], v[86:87], v[16:17], v[38:39] op_sel_hi:[1,0,1]
	v_pk_fma_f32 v[42:43], v[86:87], v[16:17], v[42:43] op_sel:[0,1,0]
	v_pk_fma_f32 v[46:47], v[86:87], v[18:19], v[46:47] op_sel_hi:[1,0,1]
	v_pk_fma_f32 v[20:21], v[12:13], v[16:17], v[20:21] op_sel_hi:[1,0,1]
	v_pk_fma_f32 v[22:23], v[14:15], v[16:17], v[22:23] op_sel_hi:[1,0,1]
	v_pk_fma_f32 v[24:25], v[12:13], v[16:17], v[24:25] op_sel:[0,1,0]
	v_pk_fma_f32 v[16:17], v[14:15], v[16:17], v[26:27] op_sel:[0,1,0]
	v_pk_fma_f32 v[26:27], v[12:13], v[18:19], v[28:29] op_sel_hi:[1,0,1]
	v_pk_fma_f32 v[18:19], v[14:15], v[18:19], v[30:31] op_sel_hi:[1,0,1]
	v_pk_fma_f32 v[28:29], v[12:13], v[84:85], v[32:33] op_sel_hi:[1,0,1]
	v_pk_fma_f32 v[30:31], v[14:15], v[84:85], v[34:35] op_sel_hi:[1,0,1]
	ds_read_b128 v[12:15], v225 offset:1664
	v_pk_fma_f32 v[82:83], v[88:89], v[84:85], v[82:83] op_sel_hi:[1,0,1]
	v_pk_fma_f32 v[50:51], v[86:87], v[84:85], v[50:51] op_sel_hi:[1,0,1]
	s_waitcnt vmcnt(2)
	v_cvt_pk_f32_fp8_e32 v[34:35], v8
	v_cvt_pk_f32_fp8_sdwa v[84:85], v8 src0_sel:WORD_1
	s_waitcnt lgkmcnt(0)
; __device__ __forceinline__ void dsa_attend(const h16* PROJ, const unsigned short* IDX, const int* CNT, h16* MIXA, unsigned char* shm, unsigned* bar, unsigned xcc, unsigned xrank) {
;     ...
; #pragma unroll
;                 for (int e = 0; e < 16; ++e) { const int slot = s0 + 8 * e + r8;
;                     if ((e & 3) == 0) __builtin_amdgcn_sched_barrier(0);
;                     const f32x4 pp = *(const f32x4*)(Pl + ((size_t)wid * 256 + slot) * 4);
;                     const f32x2 p0 = (f32x2){pp.x, pp.x}, p1 = (f32x2){pp.y, pp.y}, p2 = (f32x2){pp.z, pp.z}, p3 = (f32x2){pp.w, pp.w};
;                     const unsigned wds[4] = {vv[e].x, vv[e].y, vv[e].z, vv[e].w};
; #pragma unroll
;                     for (int w = 0; w < 4; ++w) {
;                         const f32x2 lo = __builtin_amdgcn_cvt_pk_f32_fp8((int)wds[w], false), hi = __builtin_amdgcn_cvt_pk_f32_fp8((int)wds[w], true);
;                         oa2[0][2 * w] = __builtin_elementwise_fma(lo, p0, oa2[0][2 * w]); oa2[0][2 * w + 1] = __builtin_elementwise_fma(hi, p0, oa2[0][2 * w + 1]);
;                         oa2[1][2 * w] = __builtin_elementwise_fma(lo, p1, oa2[1][2 * w]); oa2[1][2 * w + 1] = __builtin_elementwise_fma(hi, p1, oa2[1][2 * w + 1]);
;                         oa2[2][2 * w] = __builtin_elementwise_fma(lo, p2, oa2[2][2 * w]); oa2[2][2 * w + 1] = __builtin_elementwise_fma(hi, p2, oa2[2][2 * w + 1]);
;                         oa2[3][2 * w] = __builtin_elementwise_fma(lo, p3, oa2[3][2 * w]); oa2[3][2 * w + 1] = __builtin_elementwise_fma(hi, p3, oa2[3][2 * w + 1]); }
;                 }
	v_mov_b32_e32 v32, v15
	v_pk_fma_f32 v[68:69], v[34:35], v[12:13], v[68:69] op_sel_hi:[1,0,1]
	v_pk_fma_f32 v[72:73], v[34:35], v[12:13], v[72:73] op_sel:[0,1,0]
	v_pk_fma_f32 v[76:77], v[34:35], v[14:15], v[76:77] op_sel_hi:[1,0,1]
	v_pk_fma_f32 v[34:35], v[34:35], v[32:33], v[80:81] op_sel_hi:[1,0,1]
	v_pk_fma_f32 v[80:81], v[84:85], v[32:33], v[82:83] op_sel_hi:[1,0,1]
	v_cvt_pk_f32_fp8_e32 v[82:83], v9
	v_cvt_pk_f32_fp8_sdwa v[8:9], v9 src0_sel:WORD_1
	v_pk_fma_f32 v[70:71], v[84:85], v[12:13], v[70:71] op_sel_hi:[1,0,1]
	v_pk_fma_f32 v[74:75], v[84:85], v[12:13], v[74:75] op_sel:[0,1,0]
	v_pk_fma_f32 v[52:53], v[82:83], v[12:13], v[52:53] op_sel_hi:[1,0,1]
	v_pk_fma_f32 v[54:55], v[8:9], v[12:13], v[54:55] op_sel_hi:[1,0,1]
	v_pk_fma_f32 v[58:59], v[8:9], v[12:13], v[58:59] op_sel:[0,1,0]
	v_pk_fma_f32 v[62:63], v[8:9], v[14:15], v[62:63] op_sel_hi:[1,0,1]
	v_pk_fma_f32 v[66:67], v[8:9], v[32:33], v[66:67] op_sel_hi:[1,0,1]
	v_cvt_pk_f32_fp8_e32 v[8:9], v10
	v_pk_fma_f32 v[56:57], v[82:83], v[12:13], v[56:57] op_sel:[0,1,0]
	v_pk_fma_f32 v[60:61], v[82:83], v[14:15], v[60:61] op_sel_hi:[1,0,1]
	v_pk_fma_f32 v[64:65], v[82:83], v[32:33], v[64:65] op_sel_hi:[1,0,1]
	v_cvt_pk_f32_fp8_sdwa v[82:83], v10 src0_sel:WORD_1
	v_pk_fma_f32 v[36:37], v[8:9], v[12:13], v[36:37] op_sel_hi:[1,0,1]
	v_pk_fma_f32 v[40:41], v[8:9], v[12:13], v[40:41] op_sel:[0,1,0]
	v_pk_fma_f32 v[44:45], v[8:9], v[14:15], v[44:45] op_sel_hi:[1,0,1]
	v_pk_fma_f32 v[48:49], v[8:9], v[32:33], v[48:49] op_sel_hi:[1,0,1]
	v_cvt_pk_f32_fp8_e32 v[8:9], v11
	v_cvt_pk_f32_fp8_sdwa v[10:11], v11 src0_sel:WORD_1
	v_pk_fma_f32 v[78:79], v[84:85], v[14:15], v[78:79] op_sel_hi:[1,0,1]
	v_pk_fma_f32 v[38:39], v[82:83], v[12:13], v[38:39] op_sel_hi:[1,0,1]
	v_pk_fma_f32 v[42:43], v[82:83], v[12:13], v[42:43] op_sel:[0,1,0]
	v_pk_fma_f32 v[46:47], v[82:83], v[14:15], v[46:47] op_sel_hi:[1,0,1]
	v_pk_fma_f32 v[20:21], v[8:9], v[12:13], v[20:21] op_sel_hi:[1,0,1]
	v_pk_fma_f32 v[22:23], v[10:11], v[12:13], v[22:23] op_sel_hi:[1,0,1]
	v_pk_fma_f32 v[24:25], v[8:9], v[12:13], v[24:25] op_sel:[0,1,0]
	v_pk_fma_f32 v[12:13], v[10:11], v[12:13], v[16:17] op_sel:[0,1,0]
	v_pk_fma_f32 v[16:17], v[8:9], v[14:15], v[26:27] op_sel_hi:[1,0,1]
	v_pk_fma_f32 v[14:15], v[10:11], v[14:15], v[18:19] op_sel_hi:[1,0,1]
	v_pk_fma_f32 v[18:19], v[8:9], v[32:33], v[28:29] op_sel_hi:[1,0,1]
	v_pk_fma_f32 v[26:27], v[10:11], v[32:33], v[30:31] op_sel_hi:[1,0,1]
	ds_read_b128 v[8:11], v225 offset:1792
	s_waitcnt vmcnt(1)
	v_cvt_pk_f32_fp8_e32 v[30:31], v4
	v_pk_fma_f32 v[50:51], v[82:83], v[32:33], v[50:51] op_sel_hi:[1,0,1]
	v_cvt_pk_f32_fp8_sdwa v[32:33], v4 src0_sel:WORD_1
	s_waitcnt lgkmcnt(0)
	v_mov_b32_e32 v28, v11
	v_pk_fma_f32 v[68:69], v[30:31], v[8:9], v[68:69] op_sel_hi:[1,0,1]
	v_pk_fma_f32 v[72:73], v[30:31], v[8:9], v[72:73] op_sel:[0,1,0]
	v_pk_fma_f32 v[76:77], v[30:31], v[10:11], v[76:77] op_sel_hi:[1,0,1]
	v_pk_fma_f32 v[30:31], v[30:31], v[28:29], v[34:35] op_sel_hi:[1,0,1]
	v_cvt_pk_f32_fp8_e32 v[34:35], v5
	v_cvt_pk_f32_fp8_sdwa v[4:5], v5 src0_sel:WORD_1
	v_pk_fma_f32 v[70:71], v[32:33], v[8:9], v[70:71] op_sel_hi:[1,0,1]
	v_pk_fma_f32 v[74:75], v[32:33], v[8:9], v[74:75] op_sel:[0,1,0]
	v_pk_fma_f32 v[78:79], v[32:33], v[10:11], v[78:79] op_sel_hi:[1,0,1]
	v_pk_fma_f32 v[32:33], v[32:33], v[28:29], v[80:81] op_sel_hi:[1,0,1]
	v_pk_fma_f32 v[52:53], v[34:35], v[8:9], v[52:53] op_sel_hi:[1,0,1]
	v_pk_fma_f32 v[54:55], v[4:5], v[8:9], v[54:55] op_sel_hi:[1,0,1]
	v_pk_fma_f32 v[56:57], v[34:35], v[8:9], v[56:57] op_sel:[0,1,0]
	v_pk_fma_f32 v[58:59], v[4:5], v[8:9], v[58:59] op_sel:[0,1,0]
	v_pk_fma_f32 v[80:81], v[34:35], v[10:11], v[60:61] op_sel_hi:[1,0,1]
	v_pk_fma_f32 v[62:63], v[4:5], v[10:11], v[62:63] op_sel_hi:[1,0,1]
	v_pk_fma_f32 v[34:35], v[34:35], v[28:29], v[64:65] op_sel_hi:[1,0,1]
	v_pk_fma_f32 v[64:65], v[4:5], v[28:29], v[66:67] op_sel_hi:[1,0,1]
	v_cvt_pk_f32_fp8_e32 v[4:5], v6
	v_cvt_pk_f32_fp8_sdwa v[60:61], v6 src0_sel:WORD_1
	v_pk_fma_f32 v[36:37], v[4:5], v[8:9], v[36:37] op_sel_hi:[1,0,1]
	v_pk_fma_f32 v[40:41], v[4:5], v[8:9], v[40:41] op_sel:[0,1,0]
	v_pk_fma_f32 v[44:45], v[4:5], v[10:11], v[44:45] op_sel_hi:[1,0,1]
	v_pk_fma_f32 v[48:49], v[4:5], v[28:29], v[48:49] op_sel_hi:[1,0,1]
	v_cvt_pk_f32_fp8_e32 v[4:5], v7
	v_cvt_pk_f32_fp8_sdwa v[6:7], v7 src0_sel:WORD_1
	v_pk_fma_f32 v[38:39], v[60:61], v[8:9], v[38:39] op_sel_hi:[1,0,1]
	v_pk_fma_f32 v[42:43], v[60:61], v[8:9], v[42:43] op_sel:[0,1,0]
	v_pk_fma_f32 v[46:47], v[60:61], v[10:11], v[46:47] op_sel_hi:[1,0,1]
	v_pk_fma_f32 v[20:21], v[4:5], v[8:9], v[20:21] op_sel_hi:[1,0,1]
	v_pk_fma_f32 v[22:23], v[6:7], v[8:9], v[22:23] op_sel_hi:[1,0,1]
	v_pk_fma_f32 v[24:25], v[4:5], v[8:9], v[24:25] op_sel:[0,1,0]
	v_pk_fma_f32 v[8:9], v[6:7], v[8:9], v[12:13] op_sel:[0,1,0]
	v_pk_fma_f32 v[12:13], v[4:5], v[10:11], v[16:17] op_sel_hi:[1,0,1]
	v_pk_fma_f32 v[10:11], v[6:7], v[10:11], v[14:15] op_sel_hi:[1,0,1]
	v_pk_fma_f32 v[14:15], v[4:5], v[28:29], v[18:19] op_sel_hi:[1,0,1]
	v_pk_fma_f32 v[16:17], v[6:7], v[28:29], v[26:27] op_sel_hi:[1,0,1]
	ds_read_b128 v[4:7], v225 offset:1920
	s_waitcnt vmcnt(0)
	v_cvt_pk_f32_fp8_e32 v[26:27], v0
	v_pk_fma_f32 v[50:51], v[60:61], v[28:29], v[50:51] op_sel_hi:[1,0,1]
	v_cvt_pk_f32_fp8_sdwa v[28:29], v0 src0_sel:WORD_1
	v_add_u32_e32 v225, 0x800, v225
	s_waitcnt lgkmcnt(0)
; __device__ __forceinline__ void dsa_attend(const h16* PROJ, const unsigned short* IDX, const int* CNT, h16* MIXA, unsigned char* shm, unsigned* bar, unsigned xcc, unsigned xrank) {
;     ...
; #pragma unroll
;                 for (int e = 0; e < 16; ++e) { const int slot = s0 + 8 * e + r8;
;                     if ((e & 3) == 0) __builtin_amdgcn_sched_barrier(0);
;                     const f32x4 pp = *(const f32x4*)(Pl + ((size_t)wid * 256 + slot) * 4);
;                     const f32x2 p0 = (f32x2){pp.x, pp.x}, p1 = (f32x2){pp.y, pp.y}, p2 = (f32x2){pp.z, pp.z}, p3 = (f32x2){pp.w, pp.w};
;                     const unsigned wds[4] = {vv[e].x, vv[e].y, vv[e].z, vv[e].w};
; #pragma unroll
;                     for (int w = 0; w < 4; ++w) {
;                         const f32x2 lo = __builtin_amdgcn_cvt_pk_f32_fp8((int)wds[w], false), hi = __builtin_amdgcn_cvt_pk_f32_fp8((int)wds[w], true);
;                         oa2[0][2 * w] = __builtin_elementwise_fma(lo, p0, oa2[0][2 * w]); oa2[0][2 * w + 1] = __builtin_elementwise_fma(hi, p0, oa2[0][2 * w + 1]);
;                         oa2[1][2 * w] = __builtin_elementwise_fma(lo, p1, oa2[1][2 * w]); oa2[1][2 * w + 1] = __builtin_elementwise_fma(hi, p1, oa2[1][2 * w + 1]);
;                         oa2[2][2 * w] = __builtin_elementwise_fma(lo, p2, oa2[2][2 * w]); oa2[2][2 * w + 1] = __builtin_elementwise_fma(hi, p2, oa2[2][2 * w + 1]);
;                         oa2[3][2 * w] = __builtin_elementwise_fma(lo, p3, oa2[3][2 * w]); oa2[3][2 * w + 1] = __builtin_elementwise_fma(hi, p3, oa2[3][2 * w + 1]); }
;                 }
	v_mov_b32_e32 v18, v7
	v_pk_fma_f32 v[110:111], v[26:27], v[4:5], v[68:69] op_sel_hi:[1,0,1]
	v_pk_fma_f32 v[104:105], v[26:27], v[4:5], v[72:73] op_sel:[0,1,0]
	v_pk_fma_f32 v[86:87], v[26:27], v[6:7], v[76:77] op_sel_hi:[1,0,1]
	v_pk_fma_f32 v[68:69], v[26:27], v[18:19], v[30:31] op_sel_hi:[1,0,1]
	v_cvt_pk_f32_fp8_e32 v[26:27], v1
	v_cvt_pk_f32_fp8_sdwa v[0:1], v1 src0_sel:WORD_1
	v_pk_fma_f32 v[76:77], v[28:29], v[6:7], v[78:79] op_sel_hi:[1,0,1]
	v_pk_fma_f32 v[92:93], v[28:29], v[4:5], v[74:75] op_sel:[0,1,0]
	v_pk_fma_f32 v[118:119], v[26:27], v[4:5], v[52:53] op_sel_hi:[1,0,1]
	v_pk_fma_f32 v[116:117], v[0:1], v[4:5], v[54:55] op_sel_hi:[1,0,1]
	v_pk_fma_f32 v[96:97], v[0:1], v[4:5], v[58:59] op_sel:[0,1,0]
	v_pk_fma_f32 v[78:79], v[0:1], v[6:7], v[62:63] op_sel_hi:[1,0,1]
	v_pk_fma_f32 v[62:63], v[0:1], v[18:19], v[64:65] op_sel_hi:[1,0,1]
	v_cvt_pk_f32_fp8_e32 v[0:1], v2
	v_pk_fma_f32 v[98:99], v[26:27], v[4:5], v[56:57] op_sel:[0,1,0]
	v_pk_fma_f32 v[90:91], v[26:27], v[6:7], v[80:81] op_sel_hi:[1,0,1]
	v_pk_fma_f32 v[72:73], v[26:27], v[18:19], v[34:35] op_sel_hi:[1,0,1]
	v_cvt_pk_f32_fp8_sdwa v[26:27], v2 src0_sel:WORD_1
	v_pk_fma_f32 v[120:121], v[0:1], v[4:5], v[36:37] op_sel_hi:[1,0,1]
	v_pk_fma_f32 v[102:103], v[0:1], v[4:5], v[40:41] op_sel:[0,1,0]
	v_pk_fma_f32 v[82:83], v[0:1], v[6:7], v[44:45] op_sel_hi:[1,0,1]
	v_pk_fma_f32 v[74:75], v[0:1], v[18:19], v[48:49] op_sel_hi:[1,0,1]
	v_cvt_pk_f32_fp8_e32 v[0:1], v3
	v_cvt_pk_f32_fp8_sdwa v[2:3], v3 src0_sel:WORD_1
	v_pk_fma_f32 v[112:113], v[28:29], v[4:5], v[70:71] op_sel_hi:[1,0,1]
	v_pk_fma_f32 v[60:61], v[28:29], v[18:19], v[32:33] op_sel_hi:[1,0,1]
	v_pk_fma_f32 v[108:109], v[26:27], v[4:5], v[38:39] op_sel_hi:[1,0,1]
	v_pk_fma_f32 v[100:101], v[26:27], v[4:5], v[42:43] op_sel:[0,1,0]
	v_pk_fma_f32 v[80:81], v[26:27], v[6:7], v[46:47] op_sel_hi:[1,0,1]
	v_pk_fma_f32 v[64:65], v[26:27], v[18:19], v[50:51] op_sel_hi:[1,0,1]
	v_pk_fma_f32 v[122:123], v[0:1], v[4:5], v[20:21] op_sel_hi:[1,0,1]
	v_pk_fma_f32 v[114:115], v[2:3], v[4:5], v[22:23] op_sel_hi:[1,0,1]
	v_pk_fma_f32 v[106:107], v[0:1], v[4:5], v[24:25] op_sel:[0,1,0]
	v_pk_fma_f32 v[94:95], v[2:3], v[4:5], v[8:9] op_sel:[0,1,0]
	v_pk_fma_f32 v[88:89], v[0:1], v[6:7], v[12:13] op_sel_hi:[1,0,1]
	v_pk_fma_f32 v[84:85], v[2:3], v[6:7], v[10:11] op_sel_hi:[1,0,1]
	v_pk_fma_f32 v[70:71], v[0:1], v[18:19], v[14:15] op_sel_hi:[1,0,1]
	v_pk_fma_f32 v[66:67], v[2:3], v[18:19], v[16:17] op_sel_hi:[1,0,1]
	s_cbranch_scc0 .LBB0_849
; __device__ __forceinline__ void dsa_attend(const h16* PROJ, const unsigned short* IDX, const int* CNT, h16* MIXA, unsigned char* shm, unsigned* bar, unsigned xcc, unsigned xrank) {
;     ...
; #pragma unroll
;             for (int h = 0; h < 4; ++h)
; #pragma unroll
;                 for (int d = 0; d < 8; ++d) { f32x2 v = oa2[h][d];
;                     v.x += __shfl_xor(v.x, 8); v.y += __shfl_xor(v.y, 8); v.x += __shfl_xor(v.x, 16); v.y += __shfl_xor(v.y, 16); v.x += __shfl_xor(v.x, 32); v.y += __shfl_xor(v.y, 32); oa2[h][d] = v; }
;             if (r8 == 0) {
;                 h16* orow = MIXA + (size_t)tokq * DM + (g * 4) * 128 + 16 * c8;
; #pragma unroll
;                 for (int h = 0; h < 4; ++h) { h16x8 w0, w1;
; #pragma unroll
;                     for (int d = 0; d < 4; ++d) { w0[2 * d] = (h16)oa2[h][d].x; w0[2 * d + 1] = (h16)oa2[h][d].y; w1[2 * d] = (h16)oa2[h][4 + d].x; w1[2 * d + 1] = (h16)oa2[h][4 + d].y; }
;                     *(h16x8*)(orow + h * 128) = w0; *(h16x8*)(orow + h * 128 + 8) = w1; }
;             }
	s_nop 1
	v_permlane32_swap_b32_e32 v110, v86
	v_permlane32_swap_b32_e32 v111, v87
	v_permlane32_swap_b32_e32 v112, v76
	v_permlane32_swap_b32_e32 v113, v77
	v_permlane32_swap_b32_e32 v118, v90
	v_permlane32_swap_b32_e32 v119, v91
	v_permlane32_swap_b32_e32 v116, v78
	v_permlane32_swap_b32_e32 v117, v79
	v_permlane32_swap_b32_e32 v120, v82
	v_permlane32_swap_b32_e32 v121, v83
	v_permlane32_swap_b32_e32 v108, v80
	v_permlane32_swap_b32_e32 v109, v81
	v_permlane32_swap_b32_e32 v122, v88
	v_permlane32_swap_b32_e32 v123, v89
	v_permlane32_swap_b32_e32 v114, v84
	v_permlane32_swap_b32_e32 v115, v85
	v_permlane32_swap_b32_e32 v104, v68
	v_permlane32_swap_b32_e32 v105, v69
	v_permlane32_swap_b32_e32 v92, v60
	v_permlane32_swap_b32_e32 v93, v61
	v_permlane32_swap_b32_e32 v98, v72
	v_permlane32_swap_b32_e32 v99, v73
	v_permlane32_swap_b32_e32 v96, v62
	v_permlane32_swap_b32_e32 v97, v63
	v_permlane32_swap_b32_e32 v102, v74
	v_permlane32_swap_b32_e32 v103, v75
	v_permlane32_swap_b32_e32 v100, v64
	v_permlane32_swap_b32_e32 v101, v65
	v_permlane32_swap_b32_e32 v106, v70
	v_permlane32_swap_b32_e32 v107, v71
	v_permlane32_swap_b32_e32 v94, v66
	v_permlane32_swap_b32_e32 v95, v67
	v_pk_add_f32 v[110:111], v[110:111], v[86:87]
	v_pk_add_f32 v[112:113], v[112:113], v[76:77]
	v_pk_add_f32 v[118:119], v[118:119], v[90:91]
	v_pk_add_f32 v[116:117], v[116:117], v[78:79]
	v_pk_add_f32 v[120:121], v[120:121], v[82:83]
	v_pk_add_f32 v[108:109], v[108:109], v[80:81]
	v_pk_add_f32 v[122:123], v[122:123], v[88:89]
	v_pk_add_f32 v[114:115], v[114:115], v[84:85]
	v_pk_add_f32 v[104:105], v[104:105], v[68:69]
	v_pk_add_f32 v[92:93], v[92:93], v[60:61]
	v_pk_add_f32 v[98:99], v[98:99], v[72:73]
	v_pk_add_f32 v[96:97], v[96:97], v[62:63]
	v_pk_add_f32 v[102:103], v[102:103], v[74:75]
	v_pk_add_f32 v[100:101], v[100:101], v[64:65]
	v_pk_add_f32 v[106:107], v[106:107], v[70:71]
	v_pk_add_f32 v[94:95], v[94:95], v[66:67]
	s_nop 1
	v_permlane16_swap_b32_e32 v110, v104
	v_permlane16_swap_b32_e32 v111, v105
	v_permlane16_swap_b32_e32 v112, v92
	v_permlane16_swap_b32_e32 v113, v93
	v_permlane16_swap_b32_e32 v118, v98
	v_permlane16_swap_b32_e32 v119, v99
	v_permlane16_swap_b32_e32 v116, v96
	v_permlane16_swap_b32_e32 v117, v97
	v_permlane16_swap_b32_e32 v120, v102
	v_permlane16_swap_b32_e32 v121, v103
	v_permlane16_swap_b32_e32 v108, v100
	v_permlane16_swap_b32_e32 v109, v101
	v_permlane16_swap_b32_e32 v122, v106
	v_permlane16_swap_b32_e32 v123, v107
	v_permlane16_swap_b32_e32 v114, v94
	v_permlane16_swap_b32_e32 v115, v95
	v_pk_add_f32 v[110:111], v[110:111], v[104:105]
	v_pk_add_f32 v[112:113], v[112:113], v[92:93]
	v_pk_add_f32 v[118:119], v[118:119], v[98:99]
	v_pk_add_f32 v[116:117], v[116:117], v[96:97]
	v_pk_add_f32 v[120:121], v[120:121], v[102:103]
	v_pk_add_f32 v[108:109], v[108:109], v[100:101]
	v_pk_add_f32 v[122:123], v[122:123], v[106:107]
	v_pk_add_f32 v[114:115], v[114:115], v[94:95]
	s_nop 1
	v_add_f32_dpp v110, v110, v110 row_ror:8 row_mask:0xf bank_mask:0xf
	v_add_f32_dpp v111, v111, v111 row_ror:8 row_mask:0xf bank_mask:0xf
	v_add_f32_dpp v112, v112, v112 row_ror:8 row_mask:0xf bank_mask:0xf
	v_add_f32_dpp v113, v113, v113 row_ror:8 row_mask:0xf bank_mask:0xf
	v_add_f32_dpp v118, v118, v118 row_ror:8 row_mask:0xf bank_mask:0xf
	v_add_f32_dpp v119, v119, v119 row_ror:8 row_mask:0xf bank_mask:0xf
	v_add_f32_dpp v116, v116, v116 row_ror:8 row_mask:0xf bank_mask:0xf
	v_add_f32_dpp v117, v117, v117 row_ror:8 row_mask:0xf bank_mask:0xf
	v_add_f32_dpp v120, v120, v120 row_ror:8 row_mask:0xf bank_mask:0xf
	v_add_f32_dpp v121, v121, v121 row_ror:8 row_mask:0xf bank_mask:0xf
	v_add_f32_dpp v108, v108, v108 row_ror:8 row_mask:0xf bank_mask:0xf
	v_add_f32_dpp v109, v109, v109 row_ror:8 row_mask:0xf bank_mask:0xf
	v_add_f32_dpp v122, v122, v122 row_ror:8 row_mask:0xf bank_mask:0xf
	v_add_f32_dpp v123, v123, v123 row_ror:8 row_mask:0xf bank_mask:0xf
	v_add_f32_dpp v114, v114, v114 row_ror:8 row_mask:0xf bank_mask:0xf
	v_add_f32_dpp v115, v115, v115 row_ror:8 row_mask:0xf bank_mask:0xf
	v_lshl_add_u64 v[146:147], v[144:145], 0, v[146:147]
	v_and_b32_e32 v8, 48, v216
	v_lshlrev_b32_e32 v8, 4, v8
	v_mov_b32_e32 v9, 0
	v_lshl_add_u64 v[146:147], v[146:147], 0, v[8:9]
	v_cvt_pk_f16_f32 v0, v110, v111
	v_cvt_pk_f16_f32 v1, v112, v113
	v_cvt_pk_f16_f32 v2, v118, v119
	v_cvt_pk_f16_f32 v3, v116, v117
	v_cvt_pk_f16_f32 v4, v120, v121
	v_cvt_pk_f16_f32 v5, v108, v109
	v_cvt_pk_f16_f32 v6, v122, v123
	v_cvt_pk_f16_f32 v7, v114, v115
	s_mov_b64 s[50:51], exec
	s_mov_b32 exec_lo, 0xff00ff
	s_mov_b32 exec_hi, 0xff00ff
	global_store_dwordx4 v[146:147], v[0:3], off
	global_store_dwordx4 v[146:147], v[4:7], off offset:16
	s_nop 1
	s_branch .LBB0_843
